# speedup vs baseline: 1.0167x; 1.0050x over previous
; #define LAS __attribute__((address_space(3)))
; #define MFMA16(a, b, c) __builtin_amdgcn_mfma_f32_16x16x32_bf16((a), (b), (c), 0, 0, 0)
; __device__ void ret_out_phase(LAS unsigned char* lds, const bf16_t* PROJ, const bf16_t* ST, bf16_t* MIX, const float* lgf, const float* lgb, const float* ogain) {
;     ...
;                 for (int kt = 0; kt < 8; ++kt)
; #pragma unroll
;                     for (int j = 0; j < 4; ++j) { const int kl = kt2 * 128 + 16 * kt + 4 * g + j; const int d = ql - kl;
;                         const float w = d > 0 ? __expf(lf * (float)d) : (d < 0 ? __expf(lb * (float)(-d)) : 2.0f); st[kt][j] *= w; }
;             } else {
; #pragma unroll
;                 for (int kk = 0; kk < 4; ++kk) { const bf16x8 pa = pack8(st[2 * kk], st[2 * kk + 1]);
;                     LAS unsigned char* vb = buf + (32 * kk + 4 * g + q4) * RP + 8 * p4;
; #pragma unroll
;                     for (int cc = 0; cc < 16; ++cc) { const bf16x8 bfrag = tr_pair(vb + 32 * cc, vb + 16 * RP + 32 * cc); o[cc] = MFMA16(pa, bfrag, o[cc]); } }
.LBB0_34:
	v_mul_f32_e32 v0, v36, v158
	v_mul_f32_e32 v158, v37, v161
	v_mul_f32_e32 v159, v34, v159
	v_mul_f32_e32 v160, v35, v160
	v_mul_f32_e32 v34, v136, v44
	v_mul_f32_e32 v35, v137, v45
	v_mul_f32_e32 v36, v134, v42
	v_mul_f32_e32 v37, v135, v43
	v_mul_f32_e32 v40, v132, v40
	v_mul_f32_e32 v41, v133, v41
	v_mul_f32_e32 v38, v130, v38
	v_mul_f32_e32 v39, v131, v39
	v_mul_f32_e32 v144, v144, v52
	v_mul_f32_e32 v145, v145, v53
	v_mul_f32_e32 v142, v142, v50
	v_mul_f32_e32 v143, v143, v51
	v_cvt_pk_bf16_f32 v50, v38, v39
	v_cvt_pk_bf16_f32 v51, v40, v41
	v_cvt_pk_bf16_f32 v52, v36, v37
	v_cvt_pk_bf16_f32 v53, v34, v35
	ds_read_b64_tr_b16 v[36:37], v225 offset:8448
	ds_read_b64_tr_b16 v[34:35], v225
	ds_read_b64_tr_b16 v[38:39], v225 offset:32
	ds_read_b64_tr_b16 v[40:41], v225 offset:8480
	v_mul_f32_e32 v148, v148, v56
	v_mul_f32_e32 v149, v149, v57
	v_mul_f32_e32 v146, v146, v54
	v_mul_f32_e32 v147, v147, v55
	s_waitcnt lgkmcnt(2)
	v_mfma_f32_16x16x32_bf16 v[54:57], v[50:53], v[34:37], v[122:125]
	v_mul_f32_e32 v152, v152, v60
	v_mul_f32_e32 v153, v153, v61
	v_mul_f32_e32 v150, v150, v58
	s_waitcnt lgkmcnt(0)
	v_mfma_f32_16x16x32_bf16 v[34:37], v[50:53], v[38:41], v[126:129]
	ds_read_b64_tr_b16 v[38:39], v225 offset:64
	ds_read_b64_tr_b16 v[40:41], v225 offset:8512
	v_mul_f32_e32 v151, v151, v59
	v_mul_f32_e32 v156, v156, v64
	s_waitcnt lgkmcnt(0)
	v_mfma_f32_16x16x32_bf16 v[58:61], v[50:53], v[38:41], v[114:117]
	ds_read_b64_tr_b16 v[38:39], v225 offset:96
	ds_read_b64_tr_b16 v[40:41], v225 offset:8544
	v_mul_f32_e32 v157, v157, v65
	v_mul_f32_e32 v154, v154, v62
	s_waitcnt lgkmcnt(0)
	v_mfma_f32_16x16x32_bf16 v[82:85], v[50:53], v[38:41], v[82:85]
	ds_read_b64_tr_b16 v[38:39], v225 offset:128
	ds_read_b64_tr_b16 v[40:41], v225 offset:8576
	v_mul_f32_e32 v155, v155, v63
	v_mul_f32_e32 v140, v140, v48
	s_waitcnt lgkmcnt(0)
	v_mfma_f32_16x16x32_bf16 v[86:89], v[50:53], v[38:41], v[86:89]
	ds_read_b64_tr_b16 v[38:39], v225 offset:160
	ds_read_b64_tr_b16 v[40:41], v225 offset:8608
	v_mul_f32_e32 v141, v141, v49
	v_mul_f32_e32 v138, v138, v46
	s_waitcnt lgkmcnt(0)
	v_mfma_f32_16x16x32_bf16 v[110:113], v[50:53], v[38:41], v[110:113]
	ds_read_b64_tr_b16 v[38:39], v225 offset:192
	ds_read_b64_tr_b16 v[40:41], v225 offset:8640
	v_mul_f32_e32 v139, v139, v47
	s_lshl_b32 s60, s12, 10
	s_waitcnt lgkmcnt(0)
	v_mfma_f32_16x16x32_bf16 v[114:117], v[50:53], v[38:41], v[98:101]
	ds_read_b64_tr_b16 v[38:39], v225 offset:224
	ds_read_b64_tr_b16 v[40:41], v225 offset:8672
	s_mov_b32 s0, 0x358637bd
	s_add_i32 s4, s14, s10
	s_waitcnt lgkmcnt(0)
	v_mfma_f32_16x16x32_bf16 v[74:77], v[50:53], v[38:41], v[74:77]
	ds_read_b64_tr_b16 v[38:39], v225 offset:256
	ds_read_b64_tr_b16 v[40:41], v225 offset:8704
	s_mov_b32 s14, 0x3b800000
	s_mov_b32 s5, 0x800000
	s_waitcnt lgkmcnt(0)
	v_mfma_f32_16x16x32_bf16 v[78:81], v[50:53], v[38:41], v[78:81]
	ds_read_b64_tr_b16 v[38:39], v225 offset:288
	ds_read_b64_tr_b16 v[40:41], v225 offset:8736
	s_mov_b64 s[16:17], 0x9000000
	v_mov_b32_e32 v169, v1
	s_waitcnt lgkmcnt(0)
	v_mfma_f32_16x16x32_bf16 v[122:125], v[50:53], v[38:41], v[102:105]
	ds_read_b64_tr_b16 v[38:39], v225 offset:320
	ds_read_b64_tr_b16 v[40:41], v225 offset:8768
	v_mov_b32_e32 v171, v1
	v_mov_b32_e32 v173, v1
	s_waitcnt lgkmcnt(0)
	v_mfma_f32_16x16x32_bf16 v[126:129], v[50:53], v[38:41], v[94:97]
	ds_read_b64_tr_b16 v[38:39], v225 offset:352
	ds_read_b64_tr_b16 v[40:41], v225 offset:8800
	v_mov_b32_e32 v175, v1
	v_mov_b32_e32 v177, v1
	s_waitcnt lgkmcnt(0)
	v_mfma_f32_16x16x32_bf16 v[130:133], v[50:53], v[38:41], v[70:73]
	ds_read_b64_tr_b16 v[38:39], v225 offset:384
	ds_read_b64_tr_b16 v[40:41], v225 offset:8832
	v_mov_b32_e32 v179, v1
	v_mov_b32_e32 v181, v1
	s_waitcnt lgkmcnt(0)
	v_mfma_f32_16x16x32_bf16 v[46:49], v[50:53], v[38:41], v[66:69]
	ds_read_b64_tr_b16 v[38:39], v225 offset:416
	ds_read_b64_tr_b16 v[40:41], v225 offset:8864
	ds_read_b64_tr_b16 v[42:43], v225 offset:448
	ds_read_b64_tr_b16 v[44:45], v225 offset:8896
	ds_read_b64_tr_b16 v[62:63], v225 offset:480
	ds_read_b64_tr_b16 v[64:65], v225 offset:8928
	s_waitcnt lgkmcnt(4)
	v_mfma_f32_16x16x32_bf16 v[38:41], v[50:53], v[38:41], v[90:93]
	v_mov_b32_e32 v183, v1
	s_waitcnt lgkmcnt(2)
	v_mfma_f32_16x16x32_bf16 v[42:45], v[50:53], v[42:45], v[106:109]
	s_waitcnt lgkmcnt(0)
	v_mfma_f32_16x16x32_bf16 v[50:53], v[50:53], v[62:65], v[118:121]
	s_nop 0
	v_cvt_pk_bf16_f32 v106, v138, v139
	v_cvt_pk_bf16_f32 v107, v140, v141
	v_cvt_pk_bf16_f32 v108, v142, v143
	v_cvt_pk_bf16_f32 v109, v144, v145
	ds_read_b64_tr_b16 v[62:63], v225 offset:16896
	ds_read_b64_tr_b16 v[64:65], v225 offset:25344
	s_waitcnt lgkmcnt(0)
	v_mfma_f32_16x16x32_bf16 v[54:57], v[106:109], v[62:65], v[54:57]
	ds_read_b64_tr_b16 v[62:63], v225 offset:16928
	ds_read_b64_tr_b16 v[64:65], v225 offset:25376
	v_cvt_pk_bf16_f32 v118, v146, v147
	v_cvt_pk_bf16_f32 v119, v148, v149
	s_waitcnt lgkmcnt(0)
	v_mfma_f32_16x16x32_bf16 v[62:65], v[106:109], v[62:65], v[34:37]
	s_nop 2
	ds_read_b64_tr_b16 v[34:35], v225 offset:16960
	ds_read_b64_tr_b16 v[36:37], v225 offset:25408
	v_cvt_pk_bf16_f32 v120, v150, v151
	v_cvt_pk_bf16_f32 v121, v152, v153
	s_waitcnt lgkmcnt(0)
	v_mfma_f32_16x16x32_bf16 v[90:93], v[106:109], v[34:37], v[58:61]
	ds_read_b64_tr_b16 v[34:35], v225 offset:16992
	ds_read_b64_tr_b16 v[36:37], v225 offset:25440
	s_waitcnt lgkmcnt(0)
	v_mfma_f32_16x16x32_bf16 v[94:97], v[106:109], v[34:37], v[82:85]
	ds_read_b64_tr_b16 v[34:35], v225 offset:17024
	ds_read_b64_tr_b16 v[36:37], v225 offset:25472
	s_waitcnt lgkmcnt(0)
	v_mfma_f32_16x16x32_bf16 v[98:101], v[106:109], v[34:37], v[86:89]
	ds_read_b64_tr_b16 v[34:35], v225 offset:17056
	ds_read_b64_tr_b16 v[36:37], v225 offset:25504
	s_waitcnt lgkmcnt(0)
; #define LAS __attribute__((address_space(3)))
; #define MFMA16(a, b, c) __builtin_amdgcn_mfma_f32_16x16x32_bf16((a), (b), (c), 0, 0, 0)
; __device__ void ret_out_phase(LAS unsigned char* lds, const bf16_t* PROJ, const bf16_t* ST, bf16_t* MIX, const float* lgf, const float* lgb, const float* ogain) {
;     ...
; #pragma unroll
;                 for (int kk = 0; kk < 4; ++kk) { const bf16x8 pa = pack8(st[2 * kk], st[2 * kk + 1]);
;                     LAS unsigned char* vb = buf + (32 * kk + 4 * g + q4) * RP + 8 * p4;
; #pragma unroll
;                     for (int cc = 0; cc < 16; ++cc) { const bf16x8 bfrag = tr_pair(vb + 32 * cc, vb + 16 * RP + 32 * cc); o[cc] = MFMA16(pa, bfrag, o[cc]); } }
	v_mfma_f32_16x16x32_bf16 v[102:105], v[106:109], v[34:37], v[110:113]
	ds_read_b64_tr_b16 v[34:35], v225 offset:17088
	ds_read_b64_tr_b16 v[36:37], v225 offset:25536
	s_waitcnt lgkmcnt(0)
	v_mfma_f32_16x16x32_bf16 v[58:61], v[106:109], v[34:37], v[114:117]
	ds_read_b64_tr_b16 v[34:35], v225 offset:17120
	ds_read_b64_tr_b16 v[36:37], v225 offset:25568
	s_waitcnt lgkmcnt(0)
	v_mfma_f32_16x16x32_bf16 v[110:113], v[106:109], v[34:37], v[74:77]
	ds_read_b64_tr_b16 v[34:35], v225 offset:17152
	ds_read_b64_tr_b16 v[36:37], v225 offset:25600
	s_waitcnt lgkmcnt(0)
	v_mfma_f32_16x16x32_bf16 v[66:69], v[106:109], v[34:37], v[78:81]
	ds_read_b64_tr_b16 v[34:35], v225 offset:17184
	ds_read_b64_tr_b16 v[36:37], v225 offset:25632
	s_waitcnt lgkmcnt(0)
	v_mfma_f32_16x16x32_bf16 v[70:73], v[106:109], v[34:37], v[122:125]
	ds_read_b64_tr_b16 v[34:35], v225 offset:17216
	ds_read_b64_tr_b16 v[36:37], v225 offset:25664
	s_waitcnt lgkmcnt(0)
	v_mfma_f32_16x16x32_bf16 v[74:77], v[106:109], v[34:37], v[126:129]
	ds_read_b64_tr_b16 v[34:35], v225 offset:17248
	ds_read_b64_tr_b16 v[36:37], v225 offset:25696
	s_waitcnt lgkmcnt(0)
	v_mfma_f32_16x16x32_bf16 v[78:81], v[106:109], v[34:37], v[130:133]
	ds_read_b64_tr_b16 v[34:35], v225 offset:17280
	ds_read_b64_tr_b16 v[36:37], v225 offset:25728
	s_waitcnt lgkmcnt(0)
	v_mfma_f32_16x16x32_bf16 v[46:49], v[106:109], v[34:37], v[46:49]
	ds_read_b64_tr_b16 v[34:35], v225 offset:17312
	ds_read_b64_tr_b16 v[36:37], v225 offset:25760
	s_waitcnt lgkmcnt(0)
	v_mfma_f32_16x16x32_bf16 v[82:85], v[106:109], v[34:37], v[38:41]
	ds_read_b64_tr_b16 v[34:35], v225 offset:17344
	ds_read_b64_tr_b16 v[36:37], v225 offset:25792
	s_waitcnt lgkmcnt(0)
	v_mfma_f32_16x16x32_bf16 v[86:89], v[106:109], v[34:37], v[42:45]
	ds_read_b64_tr_b16 v[34:35], v225 offset:17376
	ds_read_b64_tr_b16 v[36:37], v225 offset:25824
	s_waitcnt lgkmcnt(0)
	v_mfma_f32_16x16x32_bf16 v[114:117], v[106:109], v[34:37], v[50:53]
	ds_read_b64_tr_b16 v[34:35], v225 offset:33792
	ds_read_b64_tr_b16 v[36:37], v225 offset:42240
	ds_read_b64_tr_b16 v[38:39], v225 offset:33824
	ds_read_b64_tr_b16 v[40:41], v225 offset:42272
	ds_read_b64_tr_b16 v[42:43], v225 offset:33856
	ds_read_b64_tr_b16 v[44:45], v225 offset:42304
	ds_read_b64_tr_b16 v[50:51], v225 offset:33888
	ds_read_b64_tr_b16 v[52:53], v225 offset:42336
	s_waitcnt lgkmcnt(6)
	v_mfma_f32_16x16x32_bf16 v[34:37], v[118:121], v[34:37], v[54:57]
	s_waitcnt lgkmcnt(4)
	v_mfma_f32_16x16x32_bf16 v[38:41], v[118:121], v[38:41], v[62:65]
	s_waitcnt lgkmcnt(0)
	v_mfma_f32_16x16x32_bf16 v[106:109], v[118:121], v[50:53], v[94:97]
	ds_read_b64_tr_b16 v[50:51], v225 offset:33920
	ds_read_b64_tr_b16 v[52:53], v225 offset:42368
	ds_read_b64_tr_b16 v[54:55], v225 offset:33952
	ds_read_b64_tr_b16 v[56:57], v225 offset:42400
	ds_read_b64_tr_b16 v[62:63], v225 offset:33984
	ds_read_b64_tr_b16 v[64:65], v225 offset:42432
	v_mfma_f32_16x16x32_bf16 v[42:45], v[118:121], v[42:45], v[90:93]
	s_waitcnt lgkmcnt(0)
	v_mfma_f32_16x16x32_bf16 v[58:61], v[118:121], v[62:65], v[58:61]
	ds_read_b64_tr_b16 v[62:63], v225 offset:34016
	ds_read_b64_tr_b16 v[64:65], v225 offset:42464
	ds_read_b64_tr_b16 v[90:91], v225 offset:34048
	ds_read_b64_tr_b16 v[92:93], v225 offset:42496
	s_waitcnt lgkmcnt(0)
	v_mfma_f32_16x16x32_bf16 v[66:69], v[118:121], v[90:93], v[66:69]
	ds_read_b64_tr_b16 v[90:91], v225 offset:34080
	ds_read_b64_tr_b16 v[92:93], v225 offset:42528
	s_waitcnt lgkmcnt(0)
	v_mfma_f32_16x16x32_bf16 v[70:73], v[118:121], v[90:93], v[70:73]
	ds_read_b64_tr_b16 v[90:91], v225 offset:34112
	ds_read_b64_tr_b16 v[92:93], v225 offset:42560
	s_waitcnt lgkmcnt(0)
	v_mfma_f32_16x16x32_bf16 v[74:77], v[118:121], v[90:93], v[74:77]
	ds_read_b64_tr_b16 v[90:91], v225 offset:34144
	ds_read_b64_tr_b16 v[92:93], v225 offset:42592
	s_waitcnt lgkmcnt(0)
	v_mfma_f32_16x16x32_bf16 v[78:81], v[118:121], v[90:93], v[78:81]
	ds_read_b64_tr_b16 v[90:91], v225 offset:34176
	ds_read_b64_tr_b16 v[92:93], v225 offset:42624
	s_waitcnt lgkmcnt(0)
	v_mfma_f32_16x16x32_bf16 v[90:93], v[118:121], v[90:93], v[46:49]
	s_nop 2
	ds_read_b64_tr_b16 v[46:47], v225 offset:34208
	ds_read_b64_tr_b16 v[48:49], v225 offset:42656
	s_waitcnt lgkmcnt(0)
	v_mfma_f32_16x16x32_bf16 v[94:97], v[118:121], v[46:49], v[82:85]
	ds_read_b64_tr_b16 v[46:47], v225 offset:34240
	ds_read_b64_tr_b16 v[48:49], v225 offset:42688
	v_mfma_f32_16x16x32_bf16 v[54:57], v[118:121], v[54:57], v[102:105]
	s_waitcnt lgkmcnt(0)
	v_mfma_f32_16x16x32_bf16 v[102:105], v[118:121], v[46:49], v[86:89]
	ds_read_b64_tr_b16 v[46:47], v225 offset:34272
	ds_read_b64_tr_b16 v[48:49], v225 offset:42720
	v_mfma_f32_16x16x32_bf16 v[50:53], v[118:121], v[50:53], v[98:101]
	v_mfma_f32_16x16x32_bf16 v[62:65], v[118:121], v[62:65], v[110:113]
	s_waitcnt lgkmcnt(0)
	v_mfma_f32_16x16x32_bf16 v[98:101], v[118:121], v[46:49], v[114:117]
	s_nop 0
	v_cvt_pk_bf16_f32 v110, v154, v155
	v_cvt_pk_bf16_f32 v111, v156, v157
	v_cvt_pk_bf16_f32 v112, v159, v160
	v_cvt_pk_bf16_f32 v113, v0, v158
	ds_read_b64_tr_b16 v[46:47], v225 offset:50688
	ds_read_b64_tr_b16 v[48:49], v225 offset:59136
	s_waitcnt lgkmcnt(0)
	v_mfma_f32_16x16x32_bf16 v[34:37], v[110:113], v[46:49], v[34:37]
	ds_read_b64_tr_b16 v[46:47], v225 offset:50720
	ds_read_b64_tr_b16 v[48:49], v225 offset:59168
	v_xor_b32_e32 v0, 1, v229
	s_waitcnt lgkmcnt(0)
	v_mfma_f32_16x16x32_bf16 v[38:41], v[110:113], v[46:49], v[38:41]
	ds_read_b64_tr_b16 v[46:47], v225 offset:50752
	ds_read_b64_tr_b16 v[48:49], v225 offset:59200
	s_waitcnt lgkmcnt(0)
; #define LAS __attribute__((address_space(3)))
; #define MFMA16(a, b, c) __builtin_amdgcn_mfma_f32_16x16x32_bf16((a), (b), (c), 0, 0, 0)
; __device__ void ret_out_phase(LAS unsigned char* lds, const bf16_t* PROJ, const bf16_t* ST, bf16_t* MIX, const float* lgf, const float* lgb, const float* ogain) {
;     ...
;                 for (int kk = 0; kk < 4; ++kk) { const bf16x8 pa = pack8(st[2 * kk], st[2 * kk + 1]);
;                     LAS unsigned char* vb = buf + (32 * kk + 4 * g + q4) * RP + 8 * p4;
; #pragma unroll
;                     for (int cc = 0; cc < 16; ++cc) { const bf16x8 bfrag = tr_pair(vb + 32 * cc, vb + 16 * RP + 32 * cc); o[cc] = MFMA16(pa, bfrag, o[cc]); } }
;             }
;         }
;         {
;             LAS unsigned char* sl = lds + wave * (16 * RP);
; #pragma unroll
;             for (int j = 0; j < 4; ++j) { float ss = 0.f;
; #pragma unroll
;                 for (int cc = 0; cc < 16; ++cc) ss += o[cc][j] * o[cc][j];
;                 ss += __shfl_xor(ss, 1); ss += __shfl_xor(ss, 2); ss += __shfl_xor(ss, 4); ss += __shfl_xor(ss, 8);
;                 const float rstd = rsqrtf(ss * (1.0f / 256.f) + EPS); const float* og = ogain + h * 256 + fr;
	v_mfma_f32_16x16x32_bf16 v[42:45], v[110:113], v[46:49], v[42:45]
	ds_read_b64_tr_b16 v[46:47], v225 offset:50784
	ds_read_b64_tr_b16 v[48:49], v225 offset:59232
	ds_read_b64_tr_b16 v[82:83], v225 offset:50816
	ds_read_b64_tr_b16 v[84:85], v225 offset:59264
	v_pk_mul_f32 v[128:129], v[38:39], v[38:39]
	s_waitcnt lgkmcnt(0)
	v_mfma_f32_16x16x32_bf16 v[50:53], v[110:113], v[82:85], v[50:53]
	ds_read_b64_tr_b16 v[82:83], v225 offset:50848
	ds_read_b64_tr_b16 v[84:85], v225 offset:59296
	v_pk_fma_f32 v[128:129], v[34:35], v[34:35], v[128:129]
	s_waitcnt lgkmcnt(0)
	v_mfma_f32_16x16x32_bf16 v[54:57], v[110:113], v[82:85], v[54:57]
	ds_read_b64_tr_b16 v[82:83], v225 offset:50880
	ds_read_b64_tr_b16 v[84:85], v225 offset:59328
	v_pk_fma_f32 v[128:129], v[42:43], v[42:43], v[128:129]
	s_waitcnt lgkmcnt(0)
	v_mfma_f32_16x16x32_bf16 v[58:61], v[110:113], v[82:85], v[58:61]
	ds_read_b64_tr_b16 v[82:83], v225 offset:50912
	ds_read_b64_tr_b16 v[84:85], v225 offset:59360
	s_waitcnt lgkmcnt(0)
	v_mfma_f32_16x16x32_bf16 v[62:65], v[110:113], v[82:85], v[62:65]
	ds_read_b64_tr_b16 v[82:83], v225 offset:50944
	ds_read_b64_tr_b16 v[84:85], v225 offset:59392
	s_waitcnt lgkmcnt(0)
	v_mfma_f32_16x16x32_bf16 v[66:69], v[110:113], v[82:85], v[66:69]
	ds_read_b64_tr_b16 v[82:83], v225 offset:50976
	ds_read_b64_tr_b16 v[84:85], v225 offset:59424
	s_waitcnt lgkmcnt(0)
	v_mfma_f32_16x16x32_bf16 v[70:73], v[110:113], v[82:85], v[70:73]
	ds_read_b64_tr_b16 v[82:83], v225 offset:51008
	ds_read_b64_tr_b16 v[84:85], v225 offset:59456
	s_waitcnt lgkmcnt(0)
	v_mfma_f32_16x16x32_bf16 v[74:77], v[110:113], v[82:85], v[74:77]
	ds_read_b64_tr_b16 v[82:83], v225 offset:51040
	ds_read_b64_tr_b16 v[84:85], v225 offset:59488
	s_waitcnt lgkmcnt(0)
	v_mfma_f32_16x16x32_bf16 v[78:81], v[110:113], v[82:85], v[78:81]
	ds_read_b64_tr_b16 v[82:83], v225 offset:51072
	ds_read_b64_tr_b16 v[84:85], v225 offset:59520
	ds_read_b64_tr_b16 v[86:87], v225 offset:51104
	ds_read_b64_tr_b16 v[88:89], v225 offset:59552
	s_waitcnt lgkmcnt(2)
	v_mfma_f32_16x16x32_bf16 v[82:85], v[110:113], v[82:85], v[90:93]
	s_nop 2
	ds_read_b64_tr_b16 v[90:91], v225 offset:51136
	ds_read_b64_tr_b16 v[92:93], v225 offset:59584
	s_nop 2
	v_mov_b32_e32 v130, v83
	s_waitcnt lgkmcnt(2)
	v_mfma_f32_16x16x32_bf16 v[86:89], v[110:113], v[86:89], v[94:97]
	s_nop 2
	ds_read_b64_tr_b16 v[94:95], v225 offset:51168
	ds_read_b64_tr_b16 v[96:97], v225 offset:59616
	s_nop 2
	v_mov_b32_e32 v131, v87
	s_waitcnt lgkmcnt(0)
	v_mfma_f32_16x16x32_bf16 v[94:97], v[110:113], v[94:97], v[98:101]
	v_mul_f32_e64 v130, v130, v130
	v_mul_f32_e64 v131, v131, v131
	s_nop 0
	v_and_b32_e32 v98, 64, v229
	v_add_u32_e32 v98, 64, v98
	v_cmp_lt_i32_e32 vcc, v0, v98
	v_mfma_f32_16x16x32_bf16 v[90:93], v[110:113], v[90:93], v[102:105]
	v_mov_b32_e32 v100, v74
	v_cndmask_b32_e32 v0, v229, v0, vcc
	v_lshlrev_b32_e32 v120, 2, v0
	v_xor_b32_e32 v0, 2, v229
	v_cmp_lt_i32_e32 vcc, v0, v98
	v_mov_b32_e32 v102, v82
	v_mov_b32_e32 v103, v86
	v_cndmask_b32_e32 v0, v229, v0, vcc
	v_lshlrev_b32_e32 v119, 2, v0
	v_xor_b32_e32 v0, 4, v229
	v_cmp_lt_i32_e32 vcc, v0, v98
	v_pk_mul_f32 v[122:123], v[102:103], v[102:103]
	v_mov_b32_e32 v102, v90
	v_cndmask_b32_e32 v0, v229, v0, vcc
	v_lshlrev_b32_e32 v118, 2, v0
	v_xor_b32_e32 v0, 8, v229
	v_cmp_lt_i32_e32 vcc, v0, v98
	v_lshl_add_u64 v[98:99], v[162:163], 0, s[60:61]
	v_mov_b32_e32 v103, v94
	v_cndmask_b32_e32 v0, v229, v0, vcc
	v_mfma_f32_16x16x32_bf16 v[46:49], v[110:113], v[46:49], v[106:109]
	v_lshlrev_b32_e32 v117, 2, v0
	v_pk_mul_f32 v[124:125], v[102:103], v[102:103]
	global_load_dword v116, v[98:99], off
	global_load_dword v115, v[98:99], off offset:64
	global_load_dword v114, v[98:99], off offset:128
	global_load_dword v113, v[98:99], off offset:192
	global_load_dword v112, v[98:99], off offset:256
	global_load_dword v111, v[98:99], off offset:320
	global_load_dword v110, v[98:99], off offset:384
	global_load_dword v109, v[98:99], off offset:448
	global_load_dword v108, v[98:99], off offset:512
	global_load_dword v107, v[98:99], off offset:576
	global_load_dword v106, v[98:99], off offset:640
	global_load_dword v105, v[98:99], off offset:704
	global_load_dword v104, v[98:99], off offset:768
	global_load_dword v103, v[98:99], off offset:832
	global_load_dword v102, v[98:99], off offset:896
	global_load_dword v0, v[98:99], off offset:960
	v_pk_fma_f32 v[128:129], v[46:47], v[46:47], v[128:129]
	v_mov_b32_e32 v101, v78
	v_pk_fma_f32 v[128:129], v[50:51], v[50:51], v[128:129]
	v_mov_b32_e32 v98, v75
	v_pk_fma_f32 v[128:129], v[54:55], v[54:55], v[128:129]
	v_mov_b32_e32 v99, v79
	v_pk_fma_f32 v[128:129], v[58:59], v[58:59], v[128:129]
	v_pk_mul_f32 v[100:101], v[100:101], v[100:101]
	v_pk_fma_f32 v[128:129], v[62:63], v[62:63], v[128:129]
	v_pk_mul_f32 v[126:127], v[98:99], v[98:99]
	v_pk_fma_f32 v[128:129], v[66:67], v[66:67], v[128:129]
	v_mov_b32_e32 v134, v126
	v_pk_fma_f32 v[128:129], v[70:71], v[70:71], v[128:129]
	v_mov_b32_e32 v135, v100
	v_pk_add_f32 v[128:129], v[128:129], v[134:135] op_sel:[1,0] op_sel_hi:[0,1]
	v_mov_b32_e32 v100, v127
	v_mov_b32_e32 v132, v91
	v_mov_b32_e32 v133, v95
	v_pk_add_f32 v[100:101], v[128:129], v[100:101]
	v_mov_b32_e32 v126, v130
	v_mov_b32_e32 v127, v122
	v_pk_mul_f32 v[132:133], v[132:133], v[132:133]
	v_pk_add_f32 v[100:101], v[100:101], v[126:127]
	v_mov_b32_e32 v122, v131
	v_pk_add_f32 v[100:101], v[100:101], v[122:123]
	v_mov_b32_e32 v122, v132
	v_mov_b32_e32 v123, v124
	v_pk_add_f32 v[100:101], v[100:101], v[122:123]
	v_mov_b32_e32 v124, v133
	v_pk_add_f32 v[100:101], v[100:101], v[124:125]
	ds_bpermute_b32 v123, v120, v101
	ds_bpermute_b32 v122, v120, v100
	v_pk_mul_f32 v[98:99], v[40:41], v[40:41]
	s_add_i32 s60, s13, 0x48000
	v_pk_fma_f32 v[98:99], v[36:37], v[36:37], v[98:99]
	s_waitcnt lgkmcnt(0)
; #define LAS __attribute__((address_space(3)))
; __device__ __forceinline__ unsigned cvt_pk_bf16(float lo, float hi) { const f32x2 v = {lo, hi}; const bf16v2 r = __builtin_convertvector(v, bf16v2); return __builtin_bit_cast(unsigned, r); }
; __device__ void ret_out_phase(LAS unsigned char* lds, const bf16_t* PROJ, const bf16_t* ST, bf16_t* MIX, const float* lgf, const float* lgb, const float* ogain) {
;     ...
;             for (int j = 0; j < 4; ++j) { float ss = 0.f;
; #pragma unroll
;                 for (int cc = 0; cc < 16; ++cc) ss += o[cc][j] * o[cc][j];
;                 ss += __shfl_xor(ss, 1); ss += __shfl_xor(ss, 2); ss += __shfl_xor(ss, 4); ss += __shfl_xor(ss, 8);
;                 const float rstd = rsqrtf(ss * (1.0f / 256.f) + EPS); const float* og = ogain + h * 256 + fr;
; #pragma unroll
;                 for (int cc = 0; cc < 16; ++cc) *(LAS bf16_t*)(sl + (4 * g + j) * RP + (16 * cc + fr) * 2) = (bf16_t)(cvt_pk_bf16(o[cc][j] * rstd * og[16 * cc], 0.f) & 0xffffu); }
	v_pk_add_f32 v[100:101], v[100:101], v[122:123]
	ds_bpermute_b32 v123, v119, v101
	ds_bpermute_b32 v122, v119, v100
	v_pk_fma_f32 v[98:99], v[44:45], v[44:45], v[98:99]
	s_waitcnt lgkmcnt(0)
	v_pk_add_f32 v[100:101], v[100:101], v[122:123]
	ds_bpermute_b32 v123, v118, v101
	ds_bpermute_b32 v122, v118, v100
	v_pk_fma_f32 v[98:99], v[48:49], v[48:49], v[98:99]
	s_waitcnt lgkmcnt(0)
	v_pk_add_f32 v[100:101], v[100:101], v[122:123]
	ds_bpermute_b32 v123, v117, v101
	ds_bpermute_b32 v122, v117, v100
	v_pk_fma_f32 v[98:99], v[52:53], v[52:53], v[98:99]
	s_waitcnt lgkmcnt(0)
	v_pk_add_f32 v[122:123], v[100:101], v[122:123]
	v_mov_b64_e32 v[100:101], s[0:1]
	v_pk_fma_f32 v[122:123], v[122:123], s[14:15], v[100:101] op_sel_hi:[1,0,0]
	v_pk_fma_f32 v[98:99], v[56:57], v[56:57], v[98:99]
	v_mul_f32_e32 v121, 0x4b800000, v123
	v_cmp_gt_f32_e64 s[0:1], s5, v123
	v_cmp_gt_f32_e32 vcc, s5, v122
	v_pk_fma_f32 v[98:99], v[60:61], v[60:61], v[98:99]
	v_cndmask_b32_e64 v121, v123, v121, s[0:1]
	v_rsq_f32_e32 v121, v121
	v_pk_fma_f32 v[98:99], v[64:65], v[64:65], v[98:99]
	v_mul_f32_e32 v123, 0x45800000, v121
	v_cndmask_b32_e64 v121, v121, v123, s[0:1]
	v_mul_f32_e32 v34, v34, v121
	s_waitcnt vmcnt(15)
	v_mul_f32_e32 v34, v116, v34
	v_cvt_pk_bf16_f32 v34, v34, s0
	ds_write_b16 v193, v34
	v_mul_f32_e32 v34, v38, v121
	s_waitcnt vmcnt(14)
	v_mul_f32_e32 v34, v115, v34
	v_cvt_pk_bf16_f32 v34, v34, s0
	ds_write_b16 v193, v34 offset:32
	v_mul_f32_e32 v34, v42, v121
	s_waitcnt vmcnt(13)
	v_mul_f32_e32 v34, v114, v34
	v_cvt_pk_bf16_f32 v34, v34, s0
	ds_write_b16 v193, v34 offset:64
	v_mul_f32_e32 v34, v46, v121
	s_waitcnt vmcnt(12)
	v_mul_f32_e32 v34, v113, v34
	v_cvt_pk_bf16_f32 v34, v34, s0
	ds_write_b16 v193, v34 offset:96
	v_mul_f32_e32 v34, v50, v121
	s_waitcnt vmcnt(11)
	v_mul_f32_e32 v34, v112, v34
	v_cvt_pk_bf16_f32 v34, v34, s0
	ds_write_b16 v193, v34 offset:128
	v_mul_f32_e32 v34, v54, v121
	s_waitcnt vmcnt(10)
	v_mul_f32_e32 v34, v34, v111
	v_cvt_pk_bf16_f32 v34, v34, s0
	ds_write_b16 v193, v34 offset:160
	v_mul_f32_e32 v34, v58, v121
	s_waitcnt vmcnt(9)
	v_mul_f32_e32 v34, v34, v110
	v_cvt_pk_bf16_f32 v34, v34, s0
	ds_write_b16 v193, v34 offset:192
	v_mul_f32_e32 v34, v62, v121
	s_waitcnt vmcnt(8)
	v_mul_f32_e32 v34, v34, v109
	v_cvt_pk_bf16_f32 v34, v34, s0
	ds_write_b16 v193, v34 offset:224
	v_mul_f32_e32 v34, v66, v121
	s_waitcnt vmcnt(7)
	v_mul_f32_e32 v34, v34, v108
	v_cvt_pk_bf16_f32 v34, v34, s0
	ds_write_b16 v193, v34 offset:256
	v_mul_f32_e32 v34, v70, v121
	s_waitcnt vmcnt(6)
	v_mul_f32_e32 v34, v34, v107
	v_cvt_pk_bf16_f32 v34, v34, s0
	ds_write_b16 v193, v34 offset:288
	v_mul_f32_e32 v34, v74, v121
	s_waitcnt vmcnt(5)
	v_mul_f32_e32 v34, v34, v106
	v_cvt_pk_bf16_f32 v34, v34, s0
	ds_write_b16 v193, v34 offset:320
	v_mul_f32_e32 v34, v78, v121
	s_waitcnt vmcnt(4)
	v_mul_f32_e32 v34, v34, v105
	v_cvt_pk_bf16_f32 v34, v34, s0
	ds_write_b16 v193, v34 offset:352
	v_mul_f32_e32 v34, v82, v121
	s_waitcnt vmcnt(3)
	v_mul_f32_e32 v34, v34, v104
	v_cvt_pk_bf16_f32 v34, v34, s0
	ds_write_b16 v193, v34 offset:384
	v_mul_f32_e32 v34, v86, v121
	s_waitcnt vmcnt(2)
	v_mul_f32_e32 v34, v34, v103
	v_cvt_pk_bf16_f32 v34, v34, s0
	ds_write_b16 v193, v34 offset:416
	v_mul_f32_e32 v34, v90, v121
	s_waitcnt vmcnt(1)
	v_mul_f32_e32 v34, v34, v102
	v_cvt_pk_bf16_f32 v34, v34, s0
	ds_write_b16 v193, v34 offset:448
	v_mul_f32_e32 v34, v94, v121
	s_waitcnt vmcnt(0)
	v_mul_f32_e32 v34, v34, v0
	v_cvt_pk_bf16_f32 v34, v34, s0
	ds_write_b16 v193, v34 offset:480
	v_mul_f32_e32 v34, 0x4b800000, v122
	v_cndmask_b32_e32 v34, v122, v34, vcc
	v_rsq_f32_e32 v34, v34
	v_mov_b32_e32 v46, v77
	v_pk_fma_f32 v[98:99], v[68:69], v[68:69], v[98:99]
	v_mov_b32_e32 v50, v85
	v_mul_f32_e32 v38, 0x45800000, v34
	v_cndmask_b32_e32 v34, v34, v38, vcc
	v_mul_f32_e32 v35, v35, v34
	v_mul_f32_e32 v35, v116, v35
	v_cvt_pk_bf16_f32 v35, v35, s0
	ds_write_b16 v193, v35 offset:528
	v_mul_f32_e32 v35, v39, v34
	v_mul_f32_e32 v35, v115, v35
	v_cvt_pk_bf16_f32 v35, v35, s0
	ds_write_b16 v193, v35 offset:560
	v_mul_f32_e32 v35, v43, v34
	v_mul_f32_e32 v35, v114, v35
	v_cvt_pk_bf16_f32 v35, v35, s0
	ds_write_b16 v193, v35 offset:592
	v_mul_f32_e32 v35, v47, v34
	v_mul_f32_e32 v35, v113, v35
	v_cvt_pk_bf16_f32 v35, v35, s0
	ds_write_b16 v193, v35 offset:624
	v_mul_f32_e32 v35, v51, v34
	v_mul_f32_e32 v35, v112, v35
	v_cvt_pk_bf16_f32 v35, v35, s0
	ds_write_b16 v193, v35 offset:656
	v_mul_f32_e32 v35, v55, v34
	v_mul_f32_e32 v35, v111, v35
	v_cvt_pk_bf16_f32 v35, v35, s0
	ds_write_b16 v193, v35 offset:688
	v_mul_f32_e32 v35, v59, v34
	v_mul_f32_e32 v35, v110, v35
	v_cvt_pk_bf16_f32 v35, v35, s0
	ds_write_b16 v193, v35 offset:720
	v_mul_f32_e32 v35, v63, v34
	v_mul_f32_e32 v35, v109, v35
	v_cvt_pk_bf16_f32 v35, v35, s0
	ds_write_b16 v193, v35 offset:752
	v_mul_f32_e32 v35, v67, v34
	v_mul_f32_e32 v35, v108, v35
	v_cvt_pk_bf16_f32 v35, v35, s0
	ds_write_b16 v193, v35 offset:784
	v_mul_f32_e32 v35, v71, v34
	v_mul_f32_e32 v35, v107, v35
	v_cvt_pk_bf16_f32 v35, v35, s0
	ds_write_b16 v193, v35 offset:816
	v_mul_f32_e32 v35, v75, v34
	v_mul_f32_e32 v35, v106, v35
	v_cvt_pk_bf16_f32 v35, v35, s0
	ds_write_b16 v193, v35 offset:848
	v_mul_f32_e32 v35, v79, v34
	v_mul_f32_e32 v35, v105, v35
	v_cvt_pk_bf16_f32 v35, v35, s0
	ds_write_b16 v193, v35 offset:880
	v_mul_f32_e32 v35, v83, v34
	v_mul_f32_e32 v35, v104, v35
	v_cvt_pk_bf16_f32 v35, v35, s0
	ds_write_b16 v193, v35 offset:912
	v_mul_f32_e32 v35, v87, v34
	v_mul_f32_e32 v35, v103, v35
	v_cvt_pk_bf16_f32 v35, v35, s0
	ds_write_b16 v193, v35 offset:944
	v_mul_f32_e32 v35, v91, v34
	v_mul_f32_e32 v34, v95, v34
	v_mul_f32_e32 v35, v102, v35
	v_mul_f32_e32 v34, v0, v34
	v_cvt_pk_bf16_f32 v35, v35, s0
	v_cvt_pk_bf16_f32 v34, v34, s0
	ds_write_b16 v193, v35 offset:976
	ds_write_b16 v193, v34 offset:1008
	v_mov_b32_e32 v34, v76
	v_mov_b32_e32 v35, v80
	v_mov_b32_e32 v47, v81
	v_pk_mul_f32 v[34:35], v[34:35], v[34:35]
	v_pk_mul_f32 v[46:47], v[46:47], v[46:47]
	v_pk_fma_f32 v[98:99], v[72:73], v[72:73], v[98:99]
	v_mov_b32_e32 v38, v84
	v_mov_b32_e32 v39, v88
	v_mov_b32_e32 v51, v89
	v_mov_b32_e32 v58, v46
	v_mov_b32_e32 v59, v34
	v_pk_mul_f32 v[38:39], v[38:39], v[38:39]
	v_pk_mul_f32 v[50:51], v[50:51], v[50:51]
	v_pk_add_f32 v[58:59], v[98:99], v[58:59] op_sel:[1,0] op_sel_hi:[0,1]
	v_mov_b32_e32 v34, v47
	v_mov_b32_e32 v42, v92
	v_mov_b32_e32 v43, v96
	v_mov_b32_e32 v54, v93
	v_mov_b32_e32 v55, v97
	v_pk_add_f32 v[34:35], v[58:59], v[34:35]
	v_mov_b32_e32 v46, v50
	v_mov_b32_e32 v47, v38
	v_pk_mul_f32 v[42:43], v[42:43], v[42:43]
	v_pk_mul_f32 v[54:55], v[54:55], v[54:55]
	v_pk_add_f32 v[34:35], v[34:35], v[46:47]
	v_mov_b32_e32 v38, v51
	v_pk_add_f32 v[34:35], v[34:35], v[38:39]
	v_mov_b32_e32 v38, v54
	v_mov_b32_e32 v39, v42
	v_pk_add_f32 v[34:35], v[34:35], v[38:39]
	v_mov_b32_e32 v42, v55
	v_pk_add_f32 v[34:35], v[34:35], v[42:43]
	ds_bpermute_b32 v39, v120, v35
	ds_bpermute_b32 v38, v120, v34
	s_waitcnt lgkmcnt(0)
; #define LAS __attribute__((address_space(3)))
; __device__ __forceinline__ unsigned cvt_pk_bf16(float lo, float hi) { const f32x2 v = {lo, hi}; const bf16v2 r = __builtin_convertvector(v, bf16v2); return __builtin_bit_cast(unsigned, r); }
; __device__ void ret_out_phase(LAS unsigned char* lds, const bf16_t* PROJ, const bf16_t* ST, bf16_t* MIX, const float* lgf, const float* lgb, const float* ogain) {
;     ...
;             for (int j = 0; j < 4; ++j) { float ss = 0.f;
; #pragma unroll
;                 for (int cc = 0; cc < 16; ++cc) ss += o[cc][j] * o[cc][j];
;                 ss += __shfl_xor(ss, 1); ss += __shfl_xor(ss, 2); ss += __shfl_xor(ss, 4); ss += __shfl_xor(ss, 8);
;                 const float rstd = rsqrtf(ss * (1.0f / 256.f) + EPS); const float* og = ogain + h * 256 + fr;
; #pragma unroll
;                 for (int cc = 0; cc < 16; ++cc) *(LAS bf16_t*)(sl + (4 * g + j) * RP + (16 * cc + fr) * 2) = (bf16_t)(cvt_pk_bf16(o[cc][j] * rstd * og[16 * cc], 0.f) & 0xffffu); }
;             asm volatile("s_waitcnt lgkmcnt(0)" ::: "memory");
;             const int rw = lane >> 2; const size_t tok = (size_t)qt * 128 + 16 * wave + rw;
;             const bf16_t* gp = PROJ + pj(tok, 6144 + h * 256); bf16_t* mp = MIX + tok * DM + 1024 + h * 256;
	v_pk_add_f32 v[34:35], v[34:35], v[38:39]
	ds_bpermute_b32 v39, v119, v35
	ds_bpermute_b32 v38, v119, v34
	s_waitcnt lgkmcnt(0)
	v_pk_add_f32 v[34:35], v[34:35], v[38:39]
	ds_bpermute_b32 v39, v118, v35
	ds_bpermute_b32 v38, v118, v34
	s_waitcnt lgkmcnt(0)
	v_pk_add_f32 v[34:35], v[34:35], v[38:39]
	ds_bpermute_b32 v39, v117, v35
	ds_bpermute_b32 v38, v117, v34
	s_waitcnt lgkmcnt(0)
	v_pk_add_f32 v[34:35], v[34:35], v[38:39]
	s_nop 0
	v_pk_fma_f32 v[34:35], v[34:35], s[14:15], v[100:101] op_sel_hi:[1,0,0]
	s_nop 0
	v_mul_f32_e32 v38, 0x4b800000, v35
	v_cmp_gt_f32_e64 s[0:1], s5, v35
	v_cmp_gt_f32_e32 vcc, s5, v34
	s_nop 0
	v_cndmask_b32_e64 v35, v35, v38, s[0:1]
	v_rsq_f32_e32 v35, v35
	s_nop 0
	v_mul_f32_e32 v38, 0x45800000, v35
	v_cndmask_b32_e64 v35, v35, v38, s[0:1]
	v_mul_f32_e32 v36, v36, v35
	v_mul_f32_e32 v36, v116, v36
	v_cvt_pk_bf16_f32 v36, v36, s0
	ds_write_b16 v193, v36 offset:1056
	v_mul_f32_e32 v36, v40, v35
	v_mul_f32_e32 v36, v115, v36
	v_cvt_pk_bf16_f32 v36, v36, s0
	ds_write_b16 v193, v36 offset:1088
	v_mul_f32_e32 v36, v44, v35
	v_mul_f32_e32 v36, v114, v36
	v_cvt_pk_bf16_f32 v36, v36, s0
	ds_write_b16 v193, v36 offset:1120
	v_mul_f32_e32 v36, v48, v35
	v_mul_f32_e32 v36, v113, v36
	v_cvt_pk_bf16_f32 v36, v36, s0
	ds_write_b16 v193, v36 offset:1152
	v_mul_f32_e32 v36, v52, v35
	v_mul_f32_e32 v36, v112, v36
	v_cvt_pk_bf16_f32 v36, v36, s0
	ds_write_b16 v193, v36 offset:1184
	v_mul_f32_e32 v36, v56, v35
	v_mul_f32_e32 v36, v111, v36
	v_cvt_pk_bf16_f32 v36, v36, s0
	ds_write_b16 v193, v36 offset:1216
	v_mul_f32_e32 v36, v60, v35
	v_mul_f32_e32 v36, v110, v36
	v_cvt_pk_bf16_f32 v36, v36, s0
	ds_write_b16 v193, v36 offset:1248
	v_mul_f32_e32 v36, v64, v35
	v_mul_f32_e32 v36, v109, v36
	v_cvt_pk_bf16_f32 v36, v36, s0
	ds_write_b16 v193, v36 offset:1280
	v_mul_f32_e32 v36, v68, v35
	v_mul_f32_e32 v36, v108, v36
	v_cvt_pk_bf16_f32 v36, v36, s0
	ds_write_b16 v193, v36 offset:1312
	v_mul_f32_e32 v36, v72, v35
	v_mul_f32_e32 v36, v107, v36
	v_cvt_pk_bf16_f32 v36, v36, s0
	ds_write_b16 v193, v36 offset:1344
	v_mul_f32_e32 v36, v76, v35
	v_mul_f32_e32 v36, v106, v36
	v_cvt_pk_bf16_f32 v36, v36, s0
	ds_write_b16 v193, v36 offset:1376
	v_mul_f32_e32 v36, v80, v35
	v_mul_f32_e32 v36, v105, v36
	v_cvt_pk_bf16_f32 v36, v36, s0
	ds_write_b16 v193, v36 offset:1408
	v_mul_f32_e32 v36, v84, v35
	v_mul_f32_e32 v36, v104, v36
	v_cvt_pk_bf16_f32 v36, v36, s0
	ds_write_b16 v193, v36 offset:1440
	v_mul_f32_e32 v36, v88, v35
	v_mul_f32_e32 v36, v103, v36
	v_cvt_pk_bf16_f32 v36, v36, s0
	ds_write_b16 v193, v36 offset:1472
	v_mul_f32_e32 v36, v92, v35
	v_mul_f32_e32 v35, v96, v35
	v_mul_f32_e32 v35, v0, v35
	v_cvt_pk_bf16_f32 v35, v35, s0
	ds_write_b16 v193, v35 offset:1536
	v_mul_f32_e32 v35, 0x4b800000, v34
	v_cndmask_b32_e32 v34, v34, v35, vcc
	v_rsq_f32_e32 v34, v34
	v_mul_f32_e32 v36, v102, v36
	v_cvt_pk_bf16_f32 v36, v36, s0
	ds_write_b16 v193, v36 offset:1504
	v_mul_f32_e32 v35, 0x45800000, v34
	v_cndmask_b32_e32 v34, v34, v35, vcc
	v_mul_f32_e32 v35, v37, v34
	v_mul_f32_e32 v35, v116, v35
	v_cvt_pk_bf16_f32 v35, v35, s0
	ds_write_b16 v193, v35 offset:1584
	v_mul_f32_e32 v35, v41, v34
	v_mul_f32_e32 v35, v115, v35
	v_cvt_pk_bf16_f32 v35, v35, s0
	ds_write_b16 v193, v35 offset:1616
	v_mul_f32_e32 v35, v45, v34
	v_mul_f32_e32 v35, v114, v35
	v_cvt_pk_bf16_f32 v35, v35, s0
	ds_write_b16 v193, v35 offset:1648
	v_mul_f32_e32 v35, v49, v34
	v_mul_f32_e32 v35, v113, v35
	v_cvt_pk_bf16_f32 v35, v35, s0
	ds_write_b16 v193, v35 offset:1680
	v_mul_f32_e32 v35, v53, v34
	v_mul_f32_e32 v35, v112, v35
	v_cvt_pk_bf16_f32 v35, v35, s0
	ds_write_b16 v193, v35 offset:1712
	v_mul_f32_e32 v35, v57, v34
	v_mul_f32_e32 v35, v111, v35
	v_cvt_pk_bf16_f32 v35, v35, s0
	ds_write_b16 v193, v35 offset:1744
	v_mul_f32_e32 v35, v61, v34
	v_mul_f32_e32 v35, v110, v35
	v_cvt_pk_bf16_f32 v35, v35, s0
	ds_write_b16 v193, v35 offset:1776
	v_mul_f32_e32 v35, v65, v34
	v_mul_f32_e32 v35, v109, v35
	v_cvt_pk_bf16_f32 v35, v35, s0
	ds_write_b16 v193, v35 offset:1808
	v_mul_f32_e32 v35, v69, v34
	v_mul_f32_e32 v35, v108, v35
	v_cvt_pk_bf16_f32 v35, v35, s0
	ds_write_b16 v193, v35 offset:1840
	v_mul_f32_e32 v35, v73, v34
	v_mul_f32_e32 v35, v107, v35
	v_cvt_pk_bf16_f32 v35, v35, s0
	ds_write_b16 v193, v35 offset:1872
	v_mul_f32_e32 v35, v77, v34
	v_mul_f32_e32 v35, v106, v35
	v_cvt_pk_bf16_f32 v35, v35, s0
	ds_write_b16 v193, v35 offset:1904
	v_mul_f32_e32 v35, v81, v34
	v_mul_f32_e32 v35, v105, v35
	v_cvt_pk_bf16_f32 v35, v35, s0
	ds_write_b16 v193, v35 offset:1936
	v_mul_f32_e32 v35, v85, v34
	v_mul_f32_e32 v35, v104, v35
	v_cvt_pk_bf16_f32 v35, v35, s0
	ds_write_b16 v193, v35 offset:1968
	v_mul_f32_e32 v35, v89, v34
	v_mul_f32_e32 v35, v103, v35
	v_cvt_pk_bf16_f32 v35, v35, s0
	ds_write_b16 v193, v35 offset:2000
	v_mul_f32_e32 v35, v93, v34
	v_mul_f32_e32 v35, v102, v35
	v_cvt_pk_bf16_f32 v35, v35, s0
	v_mul_f32_e32 v34, v97, v34
	ds_write_b16 v193, v35 offset:2032
	v_mul_f32_e32 v0, v0, v34
	v_mov_b32_e32 v35, s3
	v_or_b32_e32 v34, s2, v164
	v_lshl_add_u64 v[36:37], v[34:35], 0, s[60:61]
	v_lshlrev_b64 v[36:37], 9, v[36:37]
	v_cvt_pk_bf16_f32 v0, v0, s0
	v_lshl_add_u64 v[36:37], s[78:79], 0, v[36:37]
	ds_write_b16 v193, v0 offset:2064
	v_lshl_add_u64 v[38:39], v[36:37], 0, s[16:17]
	s_waitcnt lgkmcnt(0)
; #define LAS __attribute__((address_space(3)))
; __device__ __forceinline__ unsigned cvt_pk_bf16(float lo, float hi) { const f32x2 v = {lo, hi}; const bf16v2 r = __builtin_convertvector(v, bf16v2); return __builtin_bit_cast(unsigned, r); }
; __device__ __forceinline__ float bf_lo(unsigned u) { return __uint_as_float(u << 16); }
; __device__ __forceinline__ float bf_hi(unsigned u) { return __uint_as_float(u & 0xffff0000u); }
; __device__ __forceinline__ float silu_f(float g) { return g * __builtin_amdgcn_rcpf(1.0f + __expf(-g)); }
; __device__ void ret_out_phase(LAS unsigned char* lds, const bf16_t* PROJ, const bf16_t* ST, bf16_t* MIX, const float* lgf, const float* lgb, const float* ogain) {
;     ...
;             const int rw = lane >> 2; const size_t tok = (size_t)qt * 128 + 16 * wave + rw;
;             const bf16_t* gp = PROJ + pj(tok, 6144 + h * 256); bf16_t* mp = MIX + tok * DM + 1024 + h * 256;
; #pragma unroll
;             for (int i = 0; i < 8; ++i) { const int ch = (lane & 3) + 4 * i; const u32x4 y = *(const LAS u32x4*)(sl + rw * RP + 16 * ch); const u32x4 gt = *(const u32x4*)(gp + 8 * ch); u32x4 w;
; #pragma unroll
;                 for (int e = 0; e < 4; ++e) w[e] = cvt_pk_bf16(bf_lo(y[e]) * silu_f(bf_lo(gt[e])), bf_hi(y[e]) * silu_f(bf_hi(gt[e])));
;                 *(u32x4*)(mp + 8 * ch) = w; }
	v_lshl_add_u64 v[40:41], v[38:39], 0, v[168:169]
	global_load_dwordx4 v[44:47], v[40:41], off
	v_lshl_add_u64 v[124:125], v[38:39], 0, v[170:171]
	global_load_dwordx4 v[100:103], v[124:125], off
	v_lshl_add_u64 v[126:127], v[38:39], 0, v[172:173]
	global_load_dwordx4 v[104:107], v[126:127], off
	v_lshl_add_u64 v[128:129], v[38:39], 0, v[174:175]
	global_load_dwordx4 v[108:111], v[128:129], off
	v_lshl_add_u64 v[130:131], v[38:39], 0, v[176:177]
	global_load_dwordx4 v[112:115], v[130:131], off
	v_lshl_add_u64 v[132:133], v[38:39], 0, v[178:179]
	global_load_dwordx4 v[116:119], v[132:133], off
	v_lshl_add_u64 v[134:135], v[38:39], 0, v[180:181]
	global_load_dwordx4 v[120:123], v[134:135], off
	v_lshlrev_b64 v[34:35], 12, v[34:35]
	v_lshl_add_u64 v[34:35], s[76:77], 0, v[34:35]
	s_lshl_b32 s60, s12, 9
	v_lshl_add_u64 v[42:43], v[34:35], 0, s[60:61]
	ds_read_b128 v[34:37], v202
	s_waitcnt lgkmcnt(0)
	v_lshlrev_b32_e32 v50, 16, v34
	v_and_b32_e32 v51, 0xffff0000, v34
	s_waitcnt vmcnt(6)
	v_lshlrev_b32_e32 v40, 16, v44
	v_mul_f32_e32 v0, 0xbfb8aa3b, v40
	v_exp_f32_e32 v0, v0
	v_and_b32_e32 v41, 0xffff0000, v44
	v_add_f32_e32 v0, 1.0, v0
	v_rcp_f32_e32 v48, v0
	v_mul_f32_e32 v0, 0xbfb8aa3b, v41
	v_exp_f32_e32 v0, v0
	s_nop 0
	v_add_f32_e32 v0, 1.0, v0
	v_rcp_f32_e32 v49, v0
	s_nop 0
	v_pk_mul_f32 v[40:41], v[48:49], v[40:41]
	s_nop 0
	v_pk_mul_f32 v[40:41], v[40:41], v[50:51]
	v_lshlrev_b32_e32 v48, 16, v35
	v_cvt_pk_bf16_f32 v34, v40, v41
	v_lshlrev_b32_e32 v40, 16, v45
	v_mul_f32_e32 v0, 0xbfb8aa3b, v40
	v_exp_f32_e32 v0, v0
	v_and_b32_e32 v41, 0xffff0000, v45
	v_and_b32_e32 v49, 0xffff0000, v35
	v_add_f32_e32 v0, 1.0, v0
	v_rcp_f32_e32 v44, v0
	v_mul_f32_e32 v0, 0xbfb8aa3b, v41
	v_exp_f32_e32 v0, v0
	s_nop 0
	v_add_f32_e32 v0, 1.0, v0
	v_rcp_f32_e32 v45, v0
	s_nop 0
	v_pk_mul_f32 v[40:41], v[44:45], v[40:41]
	s_nop 0
	v_pk_mul_f32 v[40:41], v[40:41], v[48:49]
	v_lshlrev_b32_e32 v48, 16, v36
	v_cvt_pk_bf16_f32 v35, v40, v41
	v_lshlrev_b32_e32 v40, 16, v46
	v_mul_f32_e32 v0, 0xbfb8aa3b, v40
	v_exp_f32_e32 v0, v0
	v_and_b32_e32 v41, 0xffff0000, v46
	v_and_b32_e32 v49, 0xffff0000, v36
	v_lshlrev_b32_e32 v46, 16, v37
	v_add_f32_e32 v0, 1.0, v0
	v_rcp_f32_e32 v44, v0
	v_mul_f32_e32 v0, 0xbfb8aa3b, v41
	v_exp_f32_e32 v0, v0
	s_nop 0
	v_add_f32_e32 v0, 1.0, v0
	v_rcp_f32_e32 v45, v0
	s_nop 0
	v_pk_mul_f32 v[40:41], v[44:45], v[40:41]
	s_nop 0
	v_pk_mul_f32 v[40:41], v[40:41], v[48:49]
	s_nop 0
	v_cvt_pk_bf16_f32 v36, v40, v41
	v_lshlrev_b32_e32 v40, 16, v47
	v_mul_f32_e32 v0, 0xbfb8aa3b, v40
	v_exp_f32_e32 v0, v0
	v_and_b32_e32 v41, 0xffff0000, v47
	v_and_b32_e32 v47, 0xffff0000, v37
	v_add_f32_e32 v0, 1.0, v0
	v_rcp_f32_e32 v44, v0
	v_mul_f32_e32 v0, 0xbfb8aa3b, v41
	v_exp_f32_e32 v0, v0
	s_nop 0
	v_add_f32_e32 v0, 1.0, v0
	v_rcp_f32_e32 v45, v0
	s_nop 0
	v_pk_mul_f32 v[40:41], v[44:45], v[40:41]
	s_nop 0
	v_pk_mul_f32 v[40:41], v[40:41], v[46:47]
	s_nop 0
	v_cvt_pk_bf16_f32 v37, v40, v41
	v_lshl_add_u64 v[40:41], v[42:43], 0, v[168:169]
	global_store_dwordx4 v[40:41], v[34:37], off offset:2048
	s_nop 0
	s_nop 0
	ds_read_b128 v[34:37], v203
	s_waitcnt lgkmcnt(0)
	v_lshlrev_b32_e32 v50, 16, v34
	v_and_b32_e32 v51, 0xffff0000, v34
	s_waitcnt vmcnt(6)
	v_lshlrev_b32_e32 v40, 16, v100
	v_mul_f32_e32 v0, 0xbfb8aa3b, v40
	v_exp_f32_e32 v0, v0
	v_and_b32_e32 v41, 0xffff0000, v100
	v_add_f32_e32 v0, 1.0, v0
	v_rcp_f32_e32 v48, v0
	v_mul_f32_e32 v0, 0xbfb8aa3b, v41
	v_exp_f32_e32 v0, v0
	s_nop 0
	v_add_f32_e32 v0, 1.0, v0
	v_rcp_f32_e32 v49, v0
	s_nop 0
	v_pk_mul_f32 v[40:41], v[48:49], v[40:41]
	s_nop 0
	v_pk_mul_f32 v[40:41], v[40:41], v[50:51]
	v_lshlrev_b32_e32 v48, 16, v35
	v_cvt_pk_bf16_f32 v34, v40, v41
	v_lshlrev_b32_e32 v40, 16, v101
	v_mul_f32_e32 v0, 0xbfb8aa3b, v40
	v_exp_f32_e32 v0, v0
	v_and_b32_e32 v41, 0xffff0000, v101
	v_and_b32_e32 v49, 0xffff0000, v35
	v_add_f32_e32 v0, 1.0, v0
	v_rcp_f32_e32 v100, v0
	v_mul_f32_e32 v0, 0xbfb8aa3b, v41
	v_exp_f32_e32 v0, v0
	s_nop 0
	v_add_f32_e32 v0, 1.0, v0
	v_rcp_f32_e32 v101, v0
	s_nop 0
	v_pk_mul_f32 v[40:41], v[100:101], v[40:41]
	s_nop 0
	v_pk_mul_f32 v[40:41], v[40:41], v[48:49]
	v_lshlrev_b32_e32 v48, 16, v36
	v_cvt_pk_bf16_f32 v35, v40, v41
	v_lshlrev_b32_e32 v40, 16, v102
	v_mul_f32_e32 v0, 0xbfb8aa3b, v40
	v_exp_f32_e32 v0, v0
	v_and_b32_e32 v41, 0xffff0000, v102
	v_and_b32_e32 v49, 0xffff0000, v36
	v_lshlrev_b32_e32 v102, 16, v37
	v_add_f32_e32 v0, 1.0, v0
	v_rcp_f32_e32 v100, v0
	v_mul_f32_e32 v0, 0xbfb8aa3b, v41
	v_exp_f32_e32 v0, v0
	s_nop 0
	v_add_f32_e32 v0, 1.0, v0
	v_rcp_f32_e32 v101, v0
	s_nop 0
	v_pk_mul_f32 v[40:41], v[100:101], v[40:41]
	s_nop 0
	v_pk_mul_f32 v[40:41], v[40:41], v[48:49]
	s_nop 0
	v_cvt_pk_bf16_f32 v36, v40, v41
	v_lshlrev_b32_e32 v40, 16, v103
	v_mul_f32_e32 v0, 0xbfb8aa3b, v40
	v_exp_f32_e32 v0, v0
	v_and_b32_e32 v41, 0xffff0000, v103
	v_and_b32_e32 v103, 0xffff0000, v37
	v_add_f32_e32 v0, 1.0, v0
	v_rcp_f32_e32 v100, v0
	v_mul_f32_e32 v0, 0xbfb8aa3b, v41
	v_exp_f32_e32 v0, v0
	s_nop 0
	v_add_f32_e32 v0, 1.0, v0
	v_rcp_f32_e32 v101, v0
	s_nop 0
	v_pk_mul_f32 v[40:41], v[100:101], v[40:41]
	s_nop 0
	v_pk_mul_f32 v[40:41], v[40:41], v[102:103]
	s_nop 0
	v_cvt_pk_bf16_f32 v37, v40, v41
	v_lshl_add_u64 v[40:41], v[42:43], 0, v[170:171]
	global_store_dwordx4 v[40:41], v[34:37], off offset:2048
	s_nop 0
	s_nop 0
	ds_read_b128 v[34:37], v204
	s_waitcnt lgkmcnt(0)
	v_lshlrev_b32_e32 v50, 16, v34
	v_and_b32_e32 v51, 0xffff0000, v34
	s_waitcnt vmcnt(6)
; #define LAS __attribute__((address_space(3)))
; __device__ __forceinline__ unsigned cvt_pk_bf16(float lo, float hi) { const f32x2 v = {lo, hi}; const bf16v2 r = __builtin_convertvector(v, bf16v2); return __builtin_bit_cast(unsigned, r); }
; __device__ __forceinline__ float bf_lo(unsigned u) { return __uint_as_float(u << 16); }
; __device__ __forceinline__ float bf_hi(unsigned u) { return __uint_as_float(u & 0xffff0000u); }
; __device__ __forceinline__ float silu_f(float g) { return g * __builtin_amdgcn_rcpf(1.0f + __expf(-g)); }
; __device__ void ret_out_phase(LAS unsigned char* lds, const bf16_t* PROJ, const bf16_t* ST, bf16_t* MIX, const float* lgf, const float* lgb, const float* ogain) {
;     ...
;             const int rw = lane >> 2; const size_t tok = (size_t)qt * 128 + 16 * wave + rw;
;             const bf16_t* gp = PROJ + pj(tok, 6144 + h * 256); bf16_t* mp = MIX + tok * DM + 1024 + h * 256;
; #pragma unroll
;             for (int i = 0; i < 8; ++i) { const int ch = (lane & 3) + 4 * i; const u32x4 y = *(const LAS u32x4*)(sl + rw * RP + 16 * ch); const u32x4 gt = *(const u32x4*)(gp + 8 * ch); u32x4 w;
; #pragma unroll
;                 for (int e = 0; e < 4; ++e) w[e] = cvt_pk_bf16(bf_lo(y[e]) * silu_f(bf_lo(gt[e])), bf_hi(y[e]) * silu_f(bf_hi(gt[e])));
;                 *(u32x4*)(mp + 8 * ch) = w; }
	v_lshlrev_b32_e32 v40, 16, v104
	v_mul_f32_e32 v0, 0xbfb8aa3b, v40
	v_exp_f32_e32 v0, v0
	v_and_b32_e32 v41, 0xffff0000, v104
	v_add_f32_e32 v0, 1.0, v0
	v_rcp_f32_e32 v48, v0
	v_mul_f32_e32 v0, 0xbfb8aa3b, v41
	v_exp_f32_e32 v0, v0
	s_nop 0
	v_add_f32_e32 v0, 1.0, v0
	v_rcp_f32_e32 v49, v0
	s_nop 0
	v_pk_mul_f32 v[40:41], v[48:49], v[40:41]
	s_nop 0
	v_pk_mul_f32 v[40:41], v[40:41], v[50:51]
	v_lshlrev_b32_e32 v48, 16, v35
	v_cvt_pk_bf16_f32 v34, v40, v41
	v_lshlrev_b32_e32 v40, 16, v105
	v_mul_f32_e32 v0, 0xbfb8aa3b, v40
	v_exp_f32_e32 v0, v0
	v_and_b32_e32 v41, 0xffff0000, v105
	v_and_b32_e32 v49, 0xffff0000, v35
	v_add_f32_e32 v0, 1.0, v0
	v_rcp_f32_e32 v104, v0
	v_mul_f32_e32 v0, 0xbfb8aa3b, v41
	v_exp_f32_e32 v0, v0
	s_nop 0
	v_add_f32_e32 v0, 1.0, v0
	v_rcp_f32_e32 v105, v0
	s_nop 0
	v_pk_mul_f32 v[40:41], v[104:105], v[40:41]
	s_nop 0
	v_pk_mul_f32 v[40:41], v[40:41], v[48:49]
	v_lshlrev_b32_e32 v48, 16, v36
	v_cvt_pk_bf16_f32 v35, v40, v41
	v_lshlrev_b32_e32 v40, 16, v106
	v_mul_f32_e32 v0, 0xbfb8aa3b, v40
	v_exp_f32_e32 v0, v0
	v_and_b32_e32 v41, 0xffff0000, v106
	v_and_b32_e32 v49, 0xffff0000, v36
	v_lshlrev_b32_e32 v106, 16, v37
	v_add_f32_e32 v0, 1.0, v0
	v_rcp_f32_e32 v104, v0
	v_mul_f32_e32 v0, 0xbfb8aa3b, v41
	v_exp_f32_e32 v0, v0
	s_nop 0
	v_add_f32_e32 v0, 1.0, v0
	v_rcp_f32_e32 v105, v0
	s_nop 0
	v_pk_mul_f32 v[40:41], v[104:105], v[40:41]
	s_nop 0
	v_pk_mul_f32 v[40:41], v[40:41], v[48:49]
	s_nop 0
	v_cvt_pk_bf16_f32 v36, v40, v41
	v_lshlrev_b32_e32 v40, 16, v107
	v_mul_f32_e32 v0, 0xbfb8aa3b, v40
	v_exp_f32_e32 v0, v0
	v_and_b32_e32 v41, 0xffff0000, v107
	v_and_b32_e32 v107, 0xffff0000, v37
	v_add_f32_e32 v0, 1.0, v0
	v_rcp_f32_e32 v104, v0
	v_mul_f32_e32 v0, 0xbfb8aa3b, v41
	v_exp_f32_e32 v0, v0
	s_nop 0
	v_add_f32_e32 v0, 1.0, v0
	v_rcp_f32_e32 v105, v0
	s_nop 0
	v_pk_mul_f32 v[40:41], v[104:105], v[40:41]
	s_nop 0
	v_pk_mul_f32 v[40:41], v[40:41], v[106:107]
	s_nop 0
	v_cvt_pk_bf16_f32 v37, v40, v41
	v_lshl_add_u64 v[40:41], v[42:43], 0, v[172:173]
	global_store_dwordx4 v[40:41], v[34:37], off offset:2048
	s_nop 0
	s_nop 0
	ds_read_b128 v[34:37], v205
	s_waitcnt lgkmcnt(0)
	v_lshlrev_b32_e32 v50, 16, v34
	v_and_b32_e32 v51, 0xffff0000, v34
	s_waitcnt vmcnt(6)
	v_lshlrev_b32_e32 v40, 16, v108
	v_mul_f32_e32 v0, 0xbfb8aa3b, v40
	v_exp_f32_e32 v0, v0
	v_and_b32_e32 v41, 0xffff0000, v108
	v_add_f32_e32 v0, 1.0, v0
	v_rcp_f32_e32 v48, v0
	v_mul_f32_e32 v0, 0xbfb8aa3b, v41
	v_exp_f32_e32 v0, v0
	s_nop 0
	v_add_f32_e32 v0, 1.0, v0
	v_rcp_f32_e32 v49, v0
	s_nop 0
	v_pk_mul_f32 v[40:41], v[48:49], v[40:41]
	s_nop 0
	v_pk_mul_f32 v[40:41], v[40:41], v[50:51]
	v_lshlrev_b32_e32 v48, 16, v35
	v_cvt_pk_bf16_f32 v34, v40, v41
	v_lshlrev_b32_e32 v40, 16, v109
	v_mul_f32_e32 v0, 0xbfb8aa3b, v40
	v_exp_f32_e32 v0, v0
	v_and_b32_e32 v41, 0xffff0000, v109
	v_and_b32_e32 v49, 0xffff0000, v35
	v_add_f32_e32 v0, 1.0, v0
	v_rcp_f32_e32 v108, v0
	v_mul_f32_e32 v0, 0xbfb8aa3b, v41
	v_exp_f32_e32 v0, v0
	s_nop 0
	v_add_f32_e32 v0, 1.0, v0
	v_rcp_f32_e32 v109, v0
	s_nop 0
	v_pk_mul_f32 v[40:41], v[108:109], v[40:41]
	s_nop 0
	v_pk_mul_f32 v[40:41], v[40:41], v[48:49]
	v_lshlrev_b32_e32 v48, 16, v36
	v_cvt_pk_bf16_f32 v35, v40, v41
	v_lshlrev_b32_e32 v40, 16, v110
	v_mul_f32_e32 v0, 0xbfb8aa3b, v40
	v_exp_f32_e32 v0, v0
	v_and_b32_e32 v41, 0xffff0000, v110
	v_and_b32_e32 v49, 0xffff0000, v36
	v_lshlrev_b32_e32 v110, 16, v37
	v_add_f32_e32 v0, 1.0, v0
	v_rcp_f32_e32 v108, v0
	v_mul_f32_e32 v0, 0xbfb8aa3b, v41
	v_exp_f32_e32 v0, v0
	s_nop 0
	v_add_f32_e32 v0, 1.0, v0
	v_rcp_f32_e32 v109, v0
	s_nop 0
	v_pk_mul_f32 v[40:41], v[108:109], v[40:41]
	s_nop 0
	v_pk_mul_f32 v[40:41], v[40:41], v[48:49]
	s_nop 0
	v_cvt_pk_bf16_f32 v36, v40, v41
	v_lshlrev_b32_e32 v40, 16, v111
	v_mul_f32_e32 v0, 0xbfb8aa3b, v40
	v_exp_f32_e32 v0, v0
	v_and_b32_e32 v41, 0xffff0000, v111
	v_and_b32_e32 v111, 0xffff0000, v37
	v_add_f32_e32 v0, 1.0, v0
	v_rcp_f32_e32 v108, v0
	v_mul_f32_e32 v0, 0xbfb8aa3b, v41
	v_exp_f32_e32 v0, v0
	s_nop 0
	v_add_f32_e32 v0, 1.0, v0
	v_rcp_f32_e32 v109, v0
	s_nop 0
	v_pk_mul_f32 v[40:41], v[108:109], v[40:41]
	s_nop 0
	v_pk_mul_f32 v[40:41], v[40:41], v[110:111]
	s_nop 0
	v_cvt_pk_bf16_f32 v37, v40, v41
	v_lshl_add_u64 v[40:41], v[42:43], 0, v[174:175]
	global_store_dwordx4 v[40:41], v[34:37], off offset:2048
	s_nop 0
	s_nop 0
	ds_read_b128 v[34:37], v206
	s_waitcnt lgkmcnt(0)
	v_lshlrev_b32_e32 v50, 16, v34
	v_and_b32_e32 v51, 0xffff0000, v34
	s_waitcnt vmcnt(6)
	v_lshlrev_b32_e32 v40, 16, v112
	v_mul_f32_e32 v0, 0xbfb8aa3b, v40
	v_exp_f32_e32 v0, v0
	v_and_b32_e32 v41, 0xffff0000, v112
	v_add_f32_e32 v0, 1.0, v0
	v_rcp_f32_e32 v48, v0
	v_mul_f32_e32 v0, 0xbfb8aa3b, v41
	v_exp_f32_e32 v0, v0
	s_nop 0
	v_add_f32_e32 v0, 1.0, v0
	v_rcp_f32_e32 v49, v0
	s_nop 0
	v_pk_mul_f32 v[40:41], v[48:49], v[40:41]
	s_nop 0
	v_pk_mul_f32 v[40:41], v[40:41], v[50:51]
	v_lshlrev_b32_e32 v48, 16, v35
	v_cvt_pk_bf16_f32 v34, v40, v41
	v_lshlrev_b32_e32 v40, 16, v113
	v_mul_f32_e32 v0, 0xbfb8aa3b, v40
	v_exp_f32_e32 v0, v0
	v_and_b32_e32 v41, 0xffff0000, v113
	v_and_b32_e32 v49, 0xffff0000, v35
	v_add_f32_e32 v0, 1.0, v0
	v_rcp_f32_e32 v112, v0
	v_mul_f32_e32 v0, 0xbfb8aa3b, v41
	v_exp_f32_e32 v0, v0
	s_nop 0
	v_add_f32_e32 v0, 1.0, v0
	v_rcp_f32_e32 v113, v0
	s_nop 0
	v_pk_mul_f32 v[40:41], v[112:113], v[40:41]
	s_nop 0
	v_pk_mul_f32 v[40:41], v[40:41], v[48:49]
	v_lshlrev_b32_e32 v48, 16, v36
	v_cvt_pk_bf16_f32 v35, v40, v41
	v_lshlrev_b32_e32 v40, 16, v114
	v_mul_f32_e32 v0, 0xbfb8aa3b, v40
	v_exp_f32_e32 v0, v0
	v_and_b32_e32 v41, 0xffff0000, v114
	v_and_b32_e32 v49, 0xffff0000, v36
	v_lshlrev_b32_e32 v114, 16, v37
	v_add_f32_e32 v0, 1.0, v0
	v_rcp_f32_e32 v112, v0
	v_mul_f32_e32 v0, 0xbfb8aa3b, v41
	v_exp_f32_e32 v0, v0
	s_nop 0
	v_add_f32_e32 v0, 1.0, v0
	v_rcp_f32_e32 v113, v0
	s_nop 0
	v_pk_mul_f32 v[40:41], v[112:113], v[40:41]
	s_nop 0
	v_pk_mul_f32 v[40:41], v[40:41], v[48:49]
	s_nop 0
	v_cvt_pk_bf16_f32 v36, v40, v41
	v_lshlrev_b32_e32 v40, 16, v115
	v_mul_f32_e32 v0, 0xbfb8aa3b, v40
	v_exp_f32_e32 v0, v0
	v_and_b32_e32 v41, 0xffff0000, v115
	v_and_b32_e32 v115, 0xffff0000, v37
	v_add_f32_e32 v0, 1.0, v0
	v_rcp_f32_e32 v112, v0
	v_mul_f32_e32 v0, 0xbfb8aa3b, v41
	v_exp_f32_e32 v0, v0
	s_nop 0
	v_add_f32_e32 v0, 1.0, v0
	v_rcp_f32_e32 v113, v0
	s_nop 0
	v_pk_mul_f32 v[40:41], v[112:113], v[40:41]
	s_nop 0
	v_pk_mul_f32 v[40:41], v[40:41], v[114:115]
	s_nop 0
	v_cvt_pk_bf16_f32 v37, v40, v41
	v_lshl_add_u64 v[40:41], v[42:43], 0, v[176:177]
	global_store_dwordx4 v[40:41], v[34:37], off offset:2048
	s_nop 0
	s_nop 0
	ds_read_b128 v[34:37], v207
	s_waitcnt lgkmcnt(0)
; #define LAS __attribute__((address_space(3)))
; __device__ __forceinline__ unsigned cvt_pk_bf16(float lo, float hi) { const f32x2 v = {lo, hi}; const bf16v2 r = __builtin_convertvector(v, bf16v2); return __builtin_bit_cast(unsigned, r); }
; __device__ __forceinline__ float bf_lo(unsigned u) { return __uint_as_float(u << 16); }
; __device__ __forceinline__ float bf_hi(unsigned u) { return __uint_as_float(u & 0xffff0000u); }
; __device__ __forceinline__ float silu_f(float g) { return g * __builtin_amdgcn_rcpf(1.0f + __expf(-g)); }
; __device__ void ret_out_phase(LAS unsigned char* lds, const bf16_t* PROJ, const bf16_t* ST, bf16_t* MIX, const float* lgf, const float* lgb, const float* ogain) {
;     ...
;     for (; item < 768; item += gridDim.x) {
;     ...
;             const int rw = lane >> 2; const size_t tok = (size_t)qt * 128 + 16 * wave + rw;
;             const bf16_t* gp = PROJ + pj(tok, 6144 + h * 256); bf16_t* mp = MIX + tok * DM + 1024 + h * 256;
; #pragma unroll
;             for (int i = 0; i < 8; ++i) { const int ch = (lane & 3) + 4 * i; const u32x4 y = *(const LAS u32x4*)(sl + rw * RP + 16 * ch); const u32x4 gt = *(const u32x4*)(gp + 8 * ch); u32x4 w;
; #pragma unroll
;                 for (int e = 0; e < 4; ++e) w[e] = cvt_pk_bf16(bf_lo(y[e]) * silu_f(bf_lo(gt[e])), bf_hi(y[e]) * silu_f(bf_hi(gt[e])));
;                 *(u32x4*)(mp + 8 * ch) = w; }
;         }
;         __syncthreads();
;     }
	v_lshlrev_b32_e32 v50, 16, v34
	v_and_b32_e32 v51, 0xffff0000, v34
	s_waitcnt vmcnt(6)
	v_lshlrev_b32_e32 v40, 16, v116
	v_mul_f32_e32 v0, 0xbfb8aa3b, v40
	v_exp_f32_e32 v0, v0
	v_and_b32_e32 v41, 0xffff0000, v116
	v_add_f32_e32 v0, 1.0, v0
	v_rcp_f32_e32 v48, v0
	v_mul_f32_e32 v0, 0xbfb8aa3b, v41
	v_exp_f32_e32 v0, v0
	s_nop 0
	v_add_f32_e32 v0, 1.0, v0
	v_rcp_f32_e32 v49, v0
	s_nop 0
	v_pk_mul_f32 v[40:41], v[48:49], v[40:41]
	s_nop 0
	v_pk_mul_f32 v[40:41], v[40:41], v[50:51]
	v_lshlrev_b32_e32 v48, 16, v35
	v_cvt_pk_bf16_f32 v34, v40, v41
	v_lshlrev_b32_e32 v40, 16, v117
	v_mul_f32_e32 v0, 0xbfb8aa3b, v40
	v_exp_f32_e32 v0, v0
	v_and_b32_e32 v41, 0xffff0000, v117
	v_and_b32_e32 v49, 0xffff0000, v35
	v_add_f32_e32 v0, 1.0, v0
	v_rcp_f32_e32 v116, v0
	v_mul_f32_e32 v0, 0xbfb8aa3b, v41
	v_exp_f32_e32 v0, v0
	s_nop 0
	v_add_f32_e32 v0, 1.0, v0
	v_rcp_f32_e32 v117, v0
	s_nop 0
	v_pk_mul_f32 v[40:41], v[116:117], v[40:41]
	s_nop 0
	v_pk_mul_f32 v[40:41], v[40:41], v[48:49]
	v_lshlrev_b32_e32 v48, 16, v36
	v_cvt_pk_bf16_f32 v35, v40, v41
	v_lshlrev_b32_e32 v40, 16, v118
	v_mul_f32_e32 v0, 0xbfb8aa3b, v40
	v_exp_f32_e32 v0, v0
	v_and_b32_e32 v41, 0xffff0000, v118
	v_and_b32_e32 v49, 0xffff0000, v36
	v_lshlrev_b32_e32 v118, 16, v37
	v_add_f32_e32 v0, 1.0, v0
	v_rcp_f32_e32 v116, v0
	v_mul_f32_e32 v0, 0xbfb8aa3b, v41
	v_exp_f32_e32 v0, v0
	s_nop 0
	v_add_f32_e32 v0, 1.0, v0
	v_rcp_f32_e32 v117, v0
	s_nop 0
	v_pk_mul_f32 v[40:41], v[116:117], v[40:41]
	s_nop 0
	v_pk_mul_f32 v[40:41], v[40:41], v[48:49]
	s_nop 0
	v_cvt_pk_bf16_f32 v36, v40, v41
	v_lshlrev_b32_e32 v40, 16, v119
	v_mul_f32_e32 v0, 0xbfb8aa3b, v40
	v_exp_f32_e32 v0, v0
	v_and_b32_e32 v41, 0xffff0000, v119
	v_and_b32_e32 v119, 0xffff0000, v37
	v_add_f32_e32 v0, 1.0, v0
	v_rcp_f32_e32 v116, v0
	v_mul_f32_e32 v0, 0xbfb8aa3b, v41
	v_exp_f32_e32 v0, v0
	s_nop 0
	v_add_f32_e32 v0, 1.0, v0
	v_rcp_f32_e32 v117, v0
	s_nop 0
	v_pk_mul_f32 v[40:41], v[116:117], v[40:41]
	s_nop 0
	v_pk_mul_f32 v[40:41], v[40:41], v[118:119]
	s_nop 0
	v_cvt_pk_bf16_f32 v37, v40, v41
	v_lshl_add_u64 v[40:41], v[42:43], 0, v[178:179]
	global_store_dwordx4 v[40:41], v[34:37], off offset:2048
	s_nop 0
	s_nop 0
	ds_read_b128 v[34:37], v208
	v_lshl_add_u64 v[38:39], v[38:39], 0, v[182:183]
	s_waitcnt lgkmcnt(0)
	v_lshlrev_b32_e32 v50, 16, v34
	v_and_b32_e32 v51, 0xffff0000, v34
	s_waitcnt vmcnt(6)
	v_lshlrev_b32_e32 v40, 16, v120
	v_mul_f32_e32 v0, 0xbfb8aa3b, v40
	v_exp_f32_e32 v0, v0
	v_and_b32_e32 v41, 0xffff0000, v120
	v_add_f32_e32 v0, 1.0, v0
	v_rcp_f32_e32 v48, v0
	v_mul_f32_e32 v0, 0xbfb8aa3b, v41
	v_exp_f32_e32 v0, v0
	s_nop 0
	v_add_f32_e32 v0, 1.0, v0
	v_rcp_f32_e32 v49, v0
	s_nop 0
	v_pk_mul_f32 v[40:41], v[48:49], v[40:41]
	s_nop 0
	v_pk_mul_f32 v[40:41], v[40:41], v[50:51]
	v_lshlrev_b32_e32 v48, 16, v35
	v_cvt_pk_bf16_f32 v34, v40, v41
	v_lshlrev_b32_e32 v40, 16, v121
	v_mul_f32_e32 v0, 0xbfb8aa3b, v40
	v_exp_f32_e32 v0, v0
	v_and_b32_e32 v41, 0xffff0000, v121
	v_and_b32_e32 v49, 0xffff0000, v35
	v_add_f32_e32 v0, 1.0, v0
	v_rcp_f32_e32 v120, v0
	v_mul_f32_e32 v0, 0xbfb8aa3b, v41
	v_exp_f32_e32 v0, v0
	s_nop 0
	v_add_f32_e32 v0, 1.0, v0
	v_rcp_f32_e32 v121, v0
	s_nop 0
	v_pk_mul_f32 v[40:41], v[120:121], v[40:41]
	s_nop 0
	v_pk_mul_f32 v[40:41], v[40:41], v[48:49]
	v_lshlrev_b32_e32 v48, 16, v36
	v_cvt_pk_bf16_f32 v35, v40, v41
	v_lshlrev_b32_e32 v40, 16, v122
	v_mul_f32_e32 v0, 0xbfb8aa3b, v40
	v_exp_f32_e32 v0, v0
	v_and_b32_e32 v41, 0xffff0000, v122
	v_and_b32_e32 v49, 0xffff0000, v36
	v_lshlrev_b32_e32 v122, 16, v37
	v_add_f32_e32 v0, 1.0, v0
	v_rcp_f32_e32 v120, v0
	v_mul_f32_e32 v0, 0xbfb8aa3b, v41
	v_exp_f32_e32 v0, v0
	s_nop 0
	v_add_f32_e32 v0, 1.0, v0
	v_rcp_f32_e32 v121, v0
	s_nop 0
	v_pk_mul_f32 v[40:41], v[120:121], v[40:41]
	s_nop 0
	v_pk_mul_f32 v[40:41], v[40:41], v[48:49]
	s_nop 0
	v_cvt_pk_bf16_f32 v36, v40, v41
	v_lshlrev_b32_e32 v40, 16, v123
	v_mul_f32_e32 v0, 0xbfb8aa3b, v40
	v_exp_f32_e32 v0, v0
	v_and_b32_e32 v41, 0xffff0000, v123
	v_and_b32_e32 v123, 0xffff0000, v37
	v_add_f32_e32 v0, 1.0, v0
	v_rcp_f32_e32 v120, v0
	v_mul_f32_e32 v0, 0xbfb8aa3b, v41
	v_exp_f32_e32 v0, v0
	s_nop 0
	v_add_f32_e32 v0, 1.0, v0
	v_rcp_f32_e32 v121, v0
	s_nop 0
	v_pk_mul_f32 v[40:41], v[120:121], v[40:41]
	s_nop 0
	v_pk_mul_f32 v[40:41], v[40:41], v[122:123]
	s_nop 0
	v_cvt_pk_bf16_f32 v37, v40, v41
	v_lshl_add_u64 v[40:41], v[42:43], 0, v[180:181]
	global_store_dwordx4 v[40:41], v[34:37], off offset:2048
	global_load_dwordx4 v[38:41], v[38:39], off
	ds_read_b128 v[34:37], v209
	s_waitcnt lgkmcnt(0)
	v_lshlrev_b32_e32 v48, 16, v34
	v_and_b32_e32 v49, 0xffff0000, v34
	s_waitcnt vmcnt(0)
	v_lshlrev_b32_e32 v44, 16, v38
	v_mul_f32_e32 v0, 0xbfb8aa3b, v44
	v_exp_f32_e32 v0, v0
	v_and_b32_e32 v45, 0xffff0000, v38
	v_lshlrev_b32_e32 v38, 16, v39
	v_and_b32_e32 v39, 0xffff0000, v39
	v_add_f32_e32 v0, 1.0, v0
	v_rcp_f32_e32 v46, v0
	v_mul_f32_e32 v0, 0xbfb8aa3b, v45
	v_exp_f32_e32 v0, v0
	s_nop 0
	v_add_f32_e32 v0, 1.0, v0
	v_rcp_f32_e32 v47, v0
	v_mul_f32_e32 v0, 0xbfb8aa3b, v38
	v_exp_f32_e32 v0, v0
	v_pk_mul_f32 v[44:45], v[46:47], v[44:45]
	s_nop 0
	v_pk_mul_f32 v[44:45], v[44:45], v[48:49]
	v_add_f32_e32 v0, 1.0, v0
	v_cvt_pk_bf16_f32 v34, v44, v45
	v_rcp_f32_e32 v44, v0
	v_mul_f32_e32 v0, 0xbfb8aa3b, v39
	v_exp_f32_e32 v0, v0
	v_lshlrev_b32_e32 v46, 16, v35
	v_and_b32_e32 v47, 0xffff0000, v35
	v_add_f32_e32 v0, 1.0, v0
	v_rcp_f32_e32 v45, v0
	s_nop 0
	v_pk_mul_f32 v[38:39], v[44:45], v[38:39]
	s_nop 0
	v_pk_mul_f32 v[38:39], v[38:39], v[46:47]
	v_lshlrev_b32_e32 v46, 16, v36
	v_cvt_pk_bf16_f32 v35, v38, v39
	v_lshlrev_b32_e32 v38, 16, v40
	v_mul_f32_e32 v0, 0xbfb8aa3b, v38
	v_exp_f32_e32 v0, v0
	v_and_b32_e32 v39, 0xffff0000, v40
	v_and_b32_e32 v47, 0xffff0000, v36
	v_add_f32_e32 v0, 1.0, v0
	v_rcp_f32_e32 v44, v0
	v_mul_f32_e32 v0, 0xbfb8aa3b, v39
	v_exp_f32_e32 v0, v0
	s_nop 0
	v_add_f32_e32 v0, 1.0, v0
	v_rcp_f32_e32 v45, v0
	s_nop 0
	v_pk_mul_f32 v[38:39], v[44:45], v[38:39]
	s_nop 0
	v_pk_mul_f32 v[38:39], v[38:39], v[46:47]
	v_lshlrev_b32_e32 v44, 16, v37
	v_cvt_pk_bf16_f32 v36, v38, v39
	v_lshlrev_b32_e32 v38, 16, v41
	v_mul_f32_e32 v0, 0xbfb8aa3b, v38
	v_exp_f32_e32 v0, v0
	v_and_b32_e32 v39, 0xffff0000, v41
	v_and_b32_e32 v45, 0xffff0000, v37
	v_add_f32_e32 v0, 1.0, v0
	v_rcp_f32_e32 v40, v0
	v_mul_f32_e32 v0, 0xbfb8aa3b, v39
	v_exp_f32_e32 v0, v0
	s_nop 0
	v_add_f32_e32 v0, 1.0, v0
	v_rcp_f32_e32 v41, v0
	s_nop 0
	v_pk_mul_f32 v[38:39], v[40:41], v[38:39]
	s_nop 0
	v_pk_mul_f32 v[38:39], v[38:39], v[44:45]
	s_nop 0
	v_cvt_pk_bf16_f32 v37, v38, v39
	v_lshl_add_u64 v[38:39], v[42:43], 0, v[182:183]
	global_store_dwordx4 v[38:39], v[34:37], off offset:2048
	s_barrier
	s_load_dword s0, s[68:69], 0x10
	s_waitcnt lgkmcnt(0)
	s_lshr_b32 s0, s0, 16
	s_cmp_lg_u32 s0, 0
	s_cselect_b64 s[0:1], -1, 0
	s_cmp_lg_u64 s[0:1], 0
	s_addc_u32 s14, s4, 0
	s_cmpk_lt_i32 s14, 0x300
	s_cbranch_scc0 .LBB0_293

; #define LAS __attribute__((address_space(3)))
; __device__ __forceinline__ unsigned cvt_pk_bf16(float lo, float hi) { const f32x2 v = {lo, hi}; const bf16v2 r = __builtin_convertvector(v, bf16v2); return __builtin_bit_cast(unsigned, r); }
; __device__ __forceinline__ float bf_lo(unsigned u) { return __uint_as_float(u << 16); }
; __device__ __forceinline__ float bf_hi(unsigned u) { return __uint_as_float(u & 0xffff0000u); }
; __device__ __forceinline__ int obid() { int b = blockIdx.x; asm volatile("" : "+s"(b)); return b; }
; __device__ void ret_kv_phase(LAS unsigned char* lds, const bf16_t* PROJ, bf16_t* ST, const float* lgf, const float* lgb) {
;     ...
;     for (int item = obid(); item < 1536; item += gridDim.x) {
;         const int xq = item & 7, yq = item >> 3, chq = (yq >> 2) * 8 + xq;
;         const int dvh = yq & 1, dir = (yq >> 1) & 1, h = chq & 3, c = chq >> 2;
;         const float lg = dir ? lgb[h] : lgf[h];
;         f32x4 acc[4][4];
; #pragma unroll
;         for (int a = 0; a < 4; ++a)
; #pragma unroll
;             for (int bb = 0; bb < 4; ++bb) acc[a][bb] = (f32x4){0.f, 0.f, 0.f, 0.f};
;         for (int sub = 0; sub < 4; ++sub) {
; #pragma unroll
;             for (int it = 0; it < 4; ++it) { const int idx = tid + 512 * it, row = idx >> 5, ch = idx & 31; const size_t tok = (size_t)c * 256 + sub * 64 + row;
;                 *(LAS u32x4*)(Kl + row * 528 + ch * 16) = *(const u32x4*)(PROJ + pj(tok, 4096 + h * 256 + ch * 8)); }
; #pragma unroll
;             for (int it = 0; it < 2; ++it) { const int idx = tid + 512 * it, row = idx >> 4, ch = idx & 15; const int jl = sub * 64 + row; const size_t tok = (size_t)c * 256 + jl;
;                 const float z = __expf(lg * (float)(dir ? jl : 255 - jl));
;                 const u32x4 v = *(const u32x4*)(PROJ + pj(tok, 5120 + h * 256 + dvh * 128 + ch * 8)); u32x4 w;
; #pragma unroll
;                 for (int e = 0; e < 4; ++e) w[e] = cvt_pk_bf16(bf_lo(v[e]) * z, bf_hi(v[e]) * z);
;                 *(LAS u32x4*)(Vl + row * 272 + ch * 16) = w; }
;             __syncthreads();
.LBB0_370:
	s_ashr_i32 s1, s14, 2
	s_and_b32 s0, s14, 4
	s_and_b32 s1, s1, -8
	s_or_b32 s4, s1, s0
	s_bfe_u32 s17, s14, 0x10004
	s_and_b32 s16, s14, 3
	s_cmp_eq_u32 s17, 0
	s_cselect_b64 vcc, -1, 0
	s_and_b64 s[0:1], vcc, exec
	s_cselect_b32 s0, s40, s42
	s_cselect_b32 s1, s41, s43
	s_add_u32 s0, s0, s2
	s_addc_u32 s1, s1, s3
	s_lshl_b32 s5, s16, 2
	s_ashr_i32 s4, s4, 2
	v_mov_b32_e32 v0, s5
	s_ashr_i32 s5, s4, 31
	s_mul_i32 s6, s16, 0x6000
	global_load_dword v94, v0, s[0:1]
	s_lshl_b64 s[0:1], s[4:5], 8
	s_add_i32 s5, s6, 0x18000
	s_add_u32 s12, s0, s5
	s_addc_u32 s13, s1, 0
	v_lshl_add_u64 v[176:177], s[12:13], 0, v[68:69]
	s_and_b32 s5, s15, 0x80
	s_add_i32 s6, s6, 0x30000
	v_lshlrev_b64 v[176:177], 9, v[176:177]
	s_add_u32 s6, s0, s6
	v_lshl_add_u64 v[176:177], v[66:67], 0, v[176:177]
	s_addc_u32 s7, s1, 0
	v_add_co_u32_e64 v176, s[0:1], s33, v176
	v_or_b32_e32 v0, s5, v96
	s_nop 0
	v_addc_co_u32_e64 v177, s[0:1], 0, v177, s[0:1]
	global_load_dwordx4 v[176:179], v[176:177], off
	v_lshlrev_b32_e32 v0, 1, v0
	v_lshl_add_u64 v[92:93], s[78:79], 0, v[0:1]
	v_cndmask_b32_e32 v0, v76, v98, vcc
	v_cvt_f32_i32_e32 v0, v0
	s_or_b32 s20, s12, 64
	s_mov_b32 s21, s13
	s_mulk_i32 s17, 0x60
	v_lshl_add_u64 v[180:181], s[12:13], 0, v[70:71]
	v_lshlrev_b64 v[180:181], 9, v[180:181]
	v_lshl_add_u64 v[180:181], v[66:67], 0, v[180:181]
	v_add_co_u32_e64 v180, s[0:1], s33, v180
	s_nop 1
	v_addc_co_u32_e64 v181, s[0:1], 0, v181, s[0:1]
	global_load_dwordx4 v[180:183], v[180:181], off
	v_lshl_add_u64 v[184:185], s[12:13], 0, v[72:73]
	v_lshlrev_b64 v[184:185], 9, v[184:185]
	v_lshl_add_u64 v[184:185], v[66:67], 0, v[184:185]
	v_add_co_u32_e64 v184, s[0:1], s33, v184
	s_nop 1
	v_addc_co_u32_e64 v185, s[0:1], 0, v185, s[0:1]
	global_load_dwordx4 v[184:187], v[184:185], off
	v_lshl_add_u64 v[188:189], s[12:13], 0, v[74:75]
	v_lshlrev_b64 v[188:189], 9, v[188:189]
	v_lshl_add_u64 v[188:189], v[66:67], 0, v[188:189]
	v_add_co_u32_e64 v188, s[0:1], s33, v188
	s_nop 1
	v_addc_co_u32_e64 v189, s[0:1], 0, v189, s[0:1]
	global_load_dwordx4 v[188:191], v[188:189], off
	v_lshl_add_u64 v[192:193], s[6:7], 0, v[76:77]
	v_lshlrev_b64 v[192:193], 9, v[192:193]
	v_lshl_add_u64 v[192:193], v[92:93], 0, v[192:193]
	v_add_co_u32_e64 v192, s[0:1], s33, v192
	s_nop 1
	v_addc_co_u32_e64 v193, s[0:1], 0, v193, s[0:1]
	global_load_dwordx4 v[192:195], v[192:193], off
	v_lshl_add_u64 v[196:197], s[6:7], 0, v[78:79]
	v_lshlrev_b64 v[196:197], 9, v[196:197]
	v_lshl_add_u64 v[196:197], v[92:93], 0, v[196:197]
	v_add_co_u32_e64 v196, s[0:1], s33, v196
	s_nop 1
	v_addc_co_u32_e64 v197, s[0:1], 0, v197, s[0:1]
	global_load_dwordx4 v[196:199], v[196:197], off
	s_waitcnt vmcnt(5)
	v_mul_f32_e32 v0, v94, v0
	v_mul_f32_e32 v0, 0x3fb8aa3b, v0
	v_exp_f32_e32 v0, v0
	s_waitcnt vmcnt(5)
	ds_write_b128 v107, v[176:179]
	s_nop 0
	s_nop 0
	s_nop 0
	s_nop 0
	s_nop 1
	s_nop 0
	s_nop 0
	s_waitcnt vmcnt(4)
	ds_write_b128 v108, v[180:183]
	s_nop 0
	s_nop 0
	s_nop 0
	s_nop 0
	s_nop 1
	s_nop 0
	s_nop 0
	s_waitcnt vmcnt(3)
	ds_write_b128 v109, v[184:187]
	s_nop 0
	s_nop 0
	s_nop 0
	s_nop 0
	s_nop 1
	s_nop 0
	s_nop 0
	s_waitcnt vmcnt(2)
	ds_write_b128 v110, v[188:191]
	s_nop 0
	s_nop 0
	s_nop 0
	s_nop 0
	s_nop 1
	s_nop 0
	s_nop 0
	s_waitcnt vmcnt(1)
	v_lshlrev_b32_e32 v6, 16, v192
	v_and_b32_e32 v7, 0xffff0000, v192
	v_pk_mul_f32 v[6:7], v[0:1], v[6:7] op_sel_hi:[0,1]
	v_cvt_pk_bf16_f32 v192, v6, v7
	v_lshlrev_b32_e32 v6, 16, v193
	v_and_b32_e32 v7, 0xffff0000, v193
	v_pk_mul_f32 v[6:7], v[0:1], v[6:7] op_sel_hi:[0,1]
	v_cvt_pk_bf16_f32 v193, v6, v7
	v_lshlrev_b32_e32 v6, 16, v194
	v_and_b32_e32 v7, 0xffff0000, v194
	v_pk_mul_f32 v[6:7], v[0:1], v[6:7] op_sel_hi:[0,1]
	v_cvt_pk_bf16_f32 v194, v6, v7
	v_lshlrev_b32_e32 v6, 16, v195
	v_and_b32_e32 v7, 0xffff0000, v195
	v_pk_mul_f32 v[6:7], v[0:1], v[6:7] op_sel_hi:[0,1]
	v_cvt_pk_bf16_f32 v195, v6, v7
	ds_write_b128 v111, v[192:195] offset:33792
	s_nop 0
	s_nop 0
	s_nop 0
	s_nop 0
	v_cndmask_b32_e32 v0, v78, v99, vcc
	s_nop 0
	s_nop 0
	s_nop 0
	v_cvt_f32_i32_e32 v0, v0
	v_mul_f32_e32 v0, v94, v0
	v_mul_f32_e32 v0, 0x3fb8aa3b, v0
	v_exp_f32_e32 v0, v0
	s_waitcnt vmcnt(0)
	v_lshlrev_b32_e32 v6, 16, v196
	v_and_b32_e32 v7, 0xffff0000, v196
	v_pk_mul_f32 v[6:7], v[0:1], v[6:7] op_sel_hi:[0,1]
	v_cvt_pk_bf16_f32 v196, v6, v7
	v_lshlrev_b32_e32 v6, 16, v197
	v_and_b32_e32 v7, 0xffff0000, v197
	v_pk_mul_f32 v[6:7], v[0:1], v[6:7] op_sel_hi:[0,1]
	v_cvt_pk_bf16_f32 v197, v6, v7
	v_lshlrev_b32_e32 v6, 16, v198
	v_and_b32_e32 v7, 0xffff0000, v198
	v_pk_mul_f32 v[6:7], v[0:1], v[6:7] op_sel_hi:[0,1]
	v_cvt_pk_bf16_f32 v198, v6, v7
	v_lshlrev_b32_e32 v6, 16, v199
	v_and_b32_e32 v7, 0xffff0000, v199
	v_pk_mul_f32 v[6:7], v[0:1], v[6:7] op_sel_hi:[0,1]
	v_cvt_pk_bf16_f32 v199, v6, v7
	ds_write_b128 v112, v[196:199] offset:33792
	s_waitcnt lgkmcnt(0)
	s_barrier
; #define LAS __attribute__((address_space(3)))
; __device__ __forceinline__ unsigned cvt_pk_bf16(float lo, float hi) { const f32x2 v = {lo, hi}; const bf16v2 r = __builtin_convertvector(v, bf16v2); return __builtin_bit_cast(unsigned, r); }
; __device__ __forceinline__ float bf_lo(unsigned u) { return __uint_as_float(u << 16); }
; __device__ __forceinline__ float bf_hi(unsigned u) { return __uint_as_float(u & 0xffff0000u); }
; #define MFMA16(a, b, c) __builtin_amdgcn_mfma_f32_16x16x32_bf16((a), (b), (c), 0, 0, 0)
; __device__ void ret_kv_phase(LAS unsigned char* lds, const bf16_t* PROJ, bf16_t* ST, const float* lgf, const float* lgb) {
;     ...
;         for (int sub = 0; sub < 4; ++sub) {
; #pragma unroll
;             for (int it = 0; it < 4; ++it) { const int idx = tid + 512 * it, row = idx >> 5, ch = idx & 31; const size_t tok = (size_t)c * 256 + sub * 64 + row;
;                 *(LAS u32x4*)(Kl + row * 528 + ch * 16) = *(const u32x4*)(PROJ + pj(tok, 4096 + h * 256 + ch * 8)); }
; #pragma unroll
;             for (int it = 0; it < 2; ++it) { const int idx = tid + 512 * it, row = idx >> 4, ch = idx & 15; const int jl = sub * 64 + row; const size_t tok = (size_t)c * 256 + jl;
;                 const float z = __expf(lg * (float)(dir ? jl : 255 - jl));
;                 const u32x4 v = *(const u32x4*)(PROJ + pj(tok, 5120 + h * 256 + dvh * 128 + ch * 8)); u32x4 w;
; #pragma unroll
;                 for (int e = 0; e < 4; ++e) w[e] = cvt_pk_bf16(bf_lo(v[e]) * z, bf_hi(v[e]) * z);
;                 *(LAS u32x4*)(Vl + row * 272 + ch * 16) = w; }
;             __syncthreads();
; #pragma unroll
;             for (int ks = 0; ks < 2; ++ks) {
;                 bf16x8 af[4], bfr[4];
;                 LAS unsigned char* vb = Vl + (32 * ks + 8 * g + q4) * 272 + (wr * 64) * 2 + 8 * p4;
;                 LAS unsigned char* kb = Kl + (32 * ks + 8 * g + q4) * 528 + (wc * 64) * 2 + 8 * p4;
; #pragma unroll
;                 for (int a = 0; a < 4; ++a) af[a] = tr_pair(vb + 32 * a, vb + 4 * 272 + 32 * a);
; #pragma unroll
;                 for (int bb = 0; bb < 4; ++bb) bfr[bb] = tr_pair(kb + 32 * bb, kb + 4 * 528 + 32 * bb);
; #pragma unroll
;                 for (int a = 0; a < 4; ++a)
; #pragma unroll
;                     for (int bb = 0; bb < 4; ++bb) acc[a][bb] = MFMA16(af[a], bfr[bb], acc[a][bb]);
	v_lshl_add_u64 v[176:177], s[20:21], 0, v[68:69]
	v_lshlrev_b64 v[176:177], 9, v[176:177]
	v_lshl_add_u64 v[176:177], v[66:67], 0, v[176:177]
	v_add_co_u32_e64 v176, s[0:1], s33, v176
	s_nop 1
	v_addc_co_u32_e64 v177, s[0:1], 0, v177, s[0:1]
	global_load_dwordx4 v[176:179], v[176:177], off
	v_lshl_add_u64 v[180:181], s[20:21], 0, v[70:71]
	v_lshlrev_b64 v[180:181], 9, v[180:181]
	v_lshl_add_u64 v[180:181], v[66:67], 0, v[180:181]
	v_add_co_u32_e64 v180, s[0:1], s33, v180
	s_nop 1
	v_addc_co_u32_e64 v181, s[0:1], 0, v181, s[0:1]
	global_load_dwordx4 v[180:183], v[180:181], off
	v_lshl_add_u64 v[184:185], s[20:21], 0, v[72:73]
	v_lshlrev_b64 v[184:185], 9, v[184:185]
	v_lshl_add_u64 v[184:185], v[66:67], 0, v[184:185]
	v_add_co_u32_e64 v184, s[0:1], s33, v184
	s_nop 1
	v_addc_co_u32_e64 v185, s[0:1], 0, v185, s[0:1]
	global_load_dwordx4 v[184:187], v[184:185], off
	v_lshl_add_u64 v[188:189], s[20:21], 0, v[74:75]
	v_lshlrev_b64 v[188:189], 9, v[188:189]
	v_lshl_add_u64 v[188:189], v[66:67], 0, v[188:189]
	v_add_co_u32_e64 v188, s[0:1], s33, v188
	s_nop 1
	v_addc_co_u32_e64 v189, s[0:1], 0, v189, s[0:1]
	global_load_dwordx4 v[188:191], v[188:189], off
	v_lshl_add_u64 v[192:193], s[6:7], 0, v[80:81]
	v_lshlrev_b64 v[192:193], 9, v[192:193]
	v_lshl_add_u64 v[192:193], v[92:93], 0, v[192:193]
	v_add_co_u32_e64 v192, s[0:1], s33, v192
	s_nop 1
	v_addc_co_u32_e64 v193, s[0:1], 0, v193, s[0:1]
	global_load_dwordx4 v[192:195], v[192:193], off
	v_lshl_add_u64 v[196:197], s[6:7], 0, v[82:83]
	v_lshlrev_b64 v[196:197], 9, v[196:197]
	v_lshl_add_u64 v[196:197], v[92:93], 0, v[196:197]
	v_add_co_u32_e64 v196, s[0:1], s33, v196
	s_nop 1
	v_addc_co_u32_e64 v197, s[0:1], 0, v197, s[0:1]
	global_load_dwordx4 v[196:199], v[196:197], off
	ds_read_b64_tr_b16 v[4:5], v113 offset:34880
	ds_read_b64_tr_b16 v[2:3], v113 offset:33792
	ds_read_b64_tr_b16 v[6:7], v113 offset:33824
	ds_read_b64_tr_b16 v[8:9], v113 offset:34912
	ds_read_b64_tr_b16 v[10:11], v113 offset:33856
	ds_read_b64_tr_b16 v[12:13], v113 offset:34944
	ds_read_b64_tr_b16 v[14:15], v113 offset:33888
	ds_read_b64_tr_b16 v[16:17], v113 offset:34976
	ds_read_b64_tr_b16 v[20:21], v114 offset:2112
	ds_read_b64_tr_b16 v[18:19], v114
	ds_read_b64_tr_b16 v[22:23], v114 offset:32
	ds_read_b64_tr_b16 v[24:25], v114 offset:2144
	ds_read_b64_tr_b16 v[26:27], v114 offset:64
	ds_read_b64_tr_b16 v[28:29], v114 offset:2176
	ds_read_b64_tr_b16 v[30:31], v114 offset:96
	ds_read_b64_tr_b16 v[32:33], v114 offset:2208
	s_waitcnt lgkmcnt(6)
	v_mfma_f32_16x16x32_bf16 v[34:37], v[2:5], v[18:21], 0
	v_cndmask_b32_e32 v0, v80, v100, vcc
	v_cvt_f32_i32_e32 v0, v0
	v_mul_f32_e32 v0, v94, v0
	v_mfma_f32_16x16x32_bf16 v[116:119], v[10:13], v[18:21], 0
	v_mul_f32_e32 v0, 0x3fb8aa3b, v0
	v_exp_f32_e32 v0, v0
	s_waitcnt lgkmcnt(4)
	v_mfma_f32_16x16x32_bf16 v[38:41], v[2:5], v[22:25], 0
	s_waitcnt lgkmcnt(2)
	v_mfma_f32_16x16x32_bf16 v[42:45], v[2:5], v[26:29], 0
	s_waitcnt lgkmcnt(0)
	v_mfma_f32_16x16x32_bf16 v[46:49], v[2:5], v[30:33], 0
	v_mfma_f32_16x16x32_bf16 v[62:65], v[6:9], v[30:33], 0
	v_mfma_f32_16x16x32_bf16 v[128:131], v[10:13], v[30:33], 0
	v_mfma_f32_16x16x32_bf16 v[132:135], v[14:17], v[18:21], 0
	v_mfma_f32_16x16x32_bf16 v[136:139], v[14:17], v[22:25], 0
	v_mfma_f32_16x16x32_bf16 v[140:143], v[14:17], v[26:29], 0
	v_mfma_f32_16x16x32_bf16 v[144:147], v[14:17], v[30:33], 0
	ds_read_b64_tr_b16 v[14:15], v113 offset:42496
	ds_read_b64_tr_b16 v[16:17], v113 offset:43584
	ds_read_b64_tr_b16 v[30:31], v113 offset:42528
	ds_read_b64_tr_b16 v[32:33], v113 offset:43616
	ds_read_b64_tr_b16 v[148:149], v113 offset:42560
	ds_read_b64_tr_b16 v[150:151], v113 offset:43648
	ds_read_b64_tr_b16 v[152:153], v113 offset:42592
	ds_read_b64_tr_b16 v[154:155], v113 offset:43680
	ds_read_b64_tr_b16 v[156:157], v114 offset:16896
	ds_read_b64_tr_b16 v[158:159], v114 offset:19008
	ds_read_b64_tr_b16 v[160:161], v114 offset:16928
	ds_read_b64_tr_b16 v[162:163], v114 offset:19040
	ds_read_b64_tr_b16 v[164:165], v114 offset:16960
	ds_read_b64_tr_b16 v[166:167], v114 offset:19072
	ds_read_b64_tr_b16 v[168:169], v114 offset:16992
	ds_read_b64_tr_b16 v[170:171], v114 offset:19104
	s_waitcnt lgkmcnt(0)
	s_barrier
	v_mfma_f32_16x16x32_bf16 v[2:5], v[14:17], v[156:159], v[34:37]
	v_mfma_f32_16x16x32_bf16 v[34:37], v[148:151], v[156:159], v[116:119]
	s_nop 2
	s_nop 0
	s_nop 0
	s_nop 0
	s_nop 0
	v_mfma_f32_16x16x32_bf16 v[120:123], v[10:13], v[22:25], 0
	s_nop 0
	s_nop 0
	s_nop 0
	v_mfma_f32_16x16x32_bf16 v[50:53], v[6:9], v[18:21], 0
	s_waitcnt vmcnt(5)
	ds_write_b128 v107, v[176:179]
	s_nop 0
	s_nop 0
	s_nop 0
	s_nop 0
	v_mfma_f32_16x16x32_bf16 v[54:57], v[6:9], v[22:25], 0
	s_nop 0
	s_nop 0
	s_nop 0
	v_mfma_f32_16x16x32_bf16 v[58:61], v[6:9], v[26:29], 0
	s_waitcnt vmcnt(4)
	ds_write_b128 v108, v[180:183]
	s_nop 0
	s_nop 0
	s_nop 0
	s_nop 0
	v_mfma_f32_16x16x32_bf16 v[6:9], v[14:17], v[160:163], v[38:41]
	s_nop 0
	s_nop 0
	s_nop 0
	v_mfma_f32_16x16x32_bf16 v[38:41], v[148:151], v[160:163], v[120:123]
	s_waitcnt vmcnt(3)
	ds_write_b128 v109, v[184:187]
	s_nop 0
	s_nop 0
	s_nop 0
	s_nop 0
	v_mfma_f32_16x16x32_bf16 v[124:127], v[10:13], v[26:29], 0
	s_nop 0
	s_nop 0
	s_nop 0
	v_mfma_f32_16x16x32_bf16 v[10:13], v[14:17], v[164:167], v[42:45]
	s_or_b32 s20, s12, 0x80
	s_or_b32 s12, s12, 0xc0
	s_waitcnt vmcnt(2)
	ds_write_b128 v110, v[188:191]
	s_nop 0
	s_nop 0
	s_nop 0
	s_nop 0
	v_mfma_f32_16x16x32_bf16 v[14:17], v[14:17], v[168:171], v[46:49]
	s_nop 0
	s_nop 0
	s_nop 0
	v_mfma_f32_16x16x32_bf16 v[18:21], v[30:33], v[156:159], v[50:53]
	s_waitcnt vmcnt(1)
; #define LAS __attribute__((address_space(3)))
; __device__ __forceinline__ unsigned cvt_pk_bf16(float lo, float hi) { const f32x2 v = {lo, hi}; const bf16v2 r = __builtin_convertvector(v, bf16v2); return __builtin_bit_cast(unsigned, r); }
; __device__ __forceinline__ float bf_lo(unsigned u) { return __uint_as_float(u << 16); }
; __device__ __forceinline__ float bf_hi(unsigned u) { return __uint_as_float(u & 0xffff0000u); }
; #define MFMA16(a, b, c) __builtin_amdgcn_mfma_f32_16x16x32_bf16((a), (b), (c), 0, 0, 0)
; __device__ void ret_kv_phase(LAS unsigned char* lds, const bf16_t* PROJ, bf16_t* ST, const float* lgf, const float* lgb) {
;     ...
;             for (int it = 0; it < 2; ++it) { const int idx = tid + 512 * it, row = idx >> 4, ch = idx & 15; const int jl = sub * 64 + row; const size_t tok = (size_t)c * 256 + jl;
;                 const float z = __expf(lg * (float)(dir ? jl : 255 - jl));
;                 const u32x4 v = *(const u32x4*)(PROJ + pj(tok, 5120 + h * 256 + dvh * 128 + ch * 8)); u32x4 w;
; #pragma unroll
;                 for (int e = 0; e < 4; ++e) w[e] = cvt_pk_bf16(bf_lo(v[e]) * z, bf_hi(v[e]) * z);
;                 *(LAS u32x4*)(Vl + row * 272 + ch * 16) = w; }
;             __syncthreads();
; #pragma unroll
;             for (int ks = 0; ks < 2; ++ks) {
;                 bf16x8 af[4], bfr[4];
;                 LAS unsigned char* vb = Vl + (32 * ks + 8 * g + q4) * 272 + (wr * 64) * 2 + 8 * p4;
;                 LAS unsigned char* kb = Kl + (32 * ks + 8 * g + q4) * 528 + (wc * 64) * 2 + 8 * p4;
; #pragma unroll
;                 for (int a = 0; a < 4; ++a) af[a] = tr_pair(vb + 32 * a, vb + 4 * 272 + 32 * a);
; #pragma unroll
;                 for (int bb = 0; bb < 4; ++bb) bfr[bb] = tr_pair(kb + 32 * bb, kb + 4 * 528 + 32 * bb);
; #pragma unroll
;                 for (int a = 0; a < 4; ++a)
; #pragma unroll
;                     for (int bb = 0; bb < 4; ++bb) acc[a][bb] = MFMA16(af[a], bfr[bb], acc[a][bb]);
	v_lshlrev_b32_e32 v120, 16, v192
	v_and_b32_e32 v121, 0xffff0000, v192
	v_pk_mul_f32 v[120:121], v[0:1], v[120:121] op_sel_hi:[0,1]
	v_cvt_pk_bf16_f32 v192, v120, v121
	v_lshlrev_b32_e32 v120, 16, v193
	v_and_b32_e32 v121, 0xffff0000, v193
	v_pk_mul_f32 v[120:121], v[0:1], v[120:121] op_sel_hi:[0,1]
	v_cvt_pk_bf16_f32 v193, v120, v121
	v_lshlrev_b32_e32 v120, 16, v194
	v_and_b32_e32 v121, 0xffff0000, v194
	v_pk_mul_f32 v[120:121], v[0:1], v[120:121] op_sel_hi:[0,1]
	v_cvt_pk_bf16_f32 v194, v120, v121
	v_lshlrev_b32_e32 v120, 16, v195
	v_and_b32_e32 v121, 0xffff0000, v195
	v_pk_mul_f32 v[120:121], v[0:1], v[120:121] op_sel_hi:[0,1]
	v_cvt_pk_bf16_f32 v195, v120, v121
	ds_write_b128 v111, v[192:195] offset:33792
	s_nop 0
	s_nop 0
	s_nop 0
	s_nop 0
	v_cndmask_b32_e32 v0, v82, v101, vcc
	s_nop 0
	s_nop 0
	s_nop 0
	v_cvt_f32_i32_e32 v0, v0
	v_mfma_f32_16x16x32_bf16 v[22:25], v[30:33], v[160:163], v[54:57]
	v_mul_f32_e32 v0, v94, v0
	v_mul_f32_e32 v0, 0x3fb8aa3b, v0
	v_exp_f32_e32 v0, v0
	v_mfma_f32_16x16x32_bf16 v[26:29], v[30:33], v[164:167], v[58:61]
	s_waitcnt vmcnt(0)
	v_lshlrev_b32_e32 v120, 16, v196
	v_and_b32_e32 v121, 0xffff0000, v196
	v_pk_mul_f32 v[120:121], v[0:1], v[120:121] op_sel_hi:[0,1]
	v_cvt_pk_bf16_f32 v196, v120, v121
	v_lshlrev_b32_e32 v120, 16, v197
	v_and_b32_e32 v121, 0xffff0000, v197
	v_pk_mul_f32 v[120:121], v[0:1], v[120:121] op_sel_hi:[0,1]
	v_cvt_pk_bf16_f32 v197, v120, v121
	v_lshlrev_b32_e32 v120, 16, v198
	v_and_b32_e32 v121, 0xffff0000, v198
	v_pk_mul_f32 v[120:121], v[0:1], v[120:121] op_sel_hi:[0,1]
	v_cvt_pk_bf16_f32 v198, v120, v121
	v_lshlrev_b32_e32 v120, 16, v199
	v_and_b32_e32 v121, 0xffff0000, v199
	v_pk_mul_f32 v[120:121], v[0:1], v[120:121] op_sel_hi:[0,1]
	v_cvt_pk_bf16_f32 v199, v120, v121
	v_mfma_f32_16x16x32_bf16 v[30:33], v[30:33], v[168:171], v[62:65]
	ds_write_b128 v112, v[196:199] offset:33792
	s_waitcnt lgkmcnt(0)
	s_barrier
	v_lshl_add_u64 v[176:177], s[20:21], 0, v[68:69]
	v_lshlrev_b64 v[176:177], 9, v[176:177]
	v_lshl_add_u64 v[176:177], v[66:67], 0, v[176:177]
	v_add_co_u32_e64 v176, s[0:1], s33, v176
	s_nop 1
	v_addc_co_u32_e64 v177, s[0:1], 0, v177, s[0:1]
	global_load_dwordx4 v[176:179], v[176:177], off
	v_lshl_add_u64 v[180:181], s[20:21], 0, v[70:71]
	v_lshlrev_b64 v[180:181], 9, v[180:181]
	v_lshl_add_u64 v[180:181], v[66:67], 0, v[180:181]
	v_add_co_u32_e64 v180, s[0:1], s33, v180
	s_nop 1
	v_addc_co_u32_e64 v181, s[0:1], 0, v181, s[0:1]
	global_load_dwordx4 v[180:183], v[180:181], off
	v_lshl_add_u64 v[184:185], s[20:21], 0, v[72:73]
	v_lshlrev_b64 v[184:185], 9, v[184:185]
	v_lshl_add_u64 v[184:185], v[66:67], 0, v[184:185]
	v_add_co_u32_e64 v184, s[0:1], s33, v184
	s_nop 1
	v_addc_co_u32_e64 v185, s[0:1], 0, v185, s[0:1]
	global_load_dwordx4 v[184:187], v[184:185], off
	v_lshl_add_u64 v[188:189], s[20:21], 0, v[74:75]
	v_lshlrev_b64 v[188:189], 9, v[188:189]
	v_lshl_add_u64 v[188:189], v[66:67], 0, v[188:189]
	v_add_co_u32_e64 v188, s[0:1], s33, v188
	s_nop 1
	v_addc_co_u32_e64 v189, s[0:1], 0, v189, s[0:1]
	global_load_dwordx4 v[188:191], v[188:189], off
	v_lshl_add_u64 v[192:193], s[6:7], 0, v[84:85]
	v_lshlrev_b64 v[192:193], 9, v[192:193]
	v_lshl_add_u64 v[192:193], v[92:93], 0, v[192:193]
	v_add_co_u32_e64 v192, s[0:1], s33, v192
	s_nop 1
	v_addc_co_u32_e64 v193, s[0:1], 0, v193, s[0:1]
	global_load_dwordx4 v[192:195], v[192:193], off
	v_lshl_add_u64 v[196:197], s[6:7], 0, v[86:87]
	v_lshlrev_b64 v[196:197], 9, v[196:197]
	v_lshl_add_u64 v[196:197], v[92:93], 0, v[196:197]
	v_add_co_u32_e64 v196, s[0:1], s33, v196
	s_nop 1
	v_addc_co_u32_e64 v197, s[0:1], 0, v197, s[0:1]
	global_load_dwordx4 v[196:199], v[196:197], off
	v_mfma_f32_16x16x32_bf16 v[42:45], v[148:151], v[164:167], v[124:127]
	v_cndmask_b32_e32 v0, v84, v102, vcc
	v_cvt_f32_i32_e32 v0, v0
	v_mfma_f32_16x16x32_bf16 v[46:49], v[148:151], v[168:171], v[128:131]
	v_mul_f32_e32 v0, v94, v0
	v_mfma_f32_16x16x32_bf16 v[50:53], v[152:155], v[156:159], v[132:135]
	v_mul_f32_e32 v0, 0x3fb8aa3b, v0
	v_exp_f32_e32 v0, v0
	v_mfma_f32_16x16x32_bf16 v[54:57], v[152:155], v[160:163], v[136:139]
	v_mfma_f32_16x16x32_bf16 v[58:61], v[152:155], v[164:167], v[140:143]
	v_mfma_f32_16x16x32_bf16 v[62:65], v[152:155], v[168:171], v[144:147]
	ds_read_b64_tr_b16 v[118:119], v113 offset:34880
	ds_read_b64_tr_b16 v[116:117], v113 offset:33792
	ds_read_b64_tr_b16 v[120:121], v113 offset:33824
	ds_read_b64_tr_b16 v[122:123], v113 offset:34912
	ds_read_b64_tr_b16 v[124:125], v113 offset:33856
	ds_read_b64_tr_b16 v[126:127], v113 offset:34944
	ds_read_b64_tr_b16 v[128:129], v113 offset:33888
	ds_read_b64_tr_b16 v[130:131], v113 offset:34976
	ds_read_b64_tr_b16 v[134:135], v114 offset:2112
	ds_read_b64_tr_b16 v[132:133], v114
	ds_read_b64_tr_b16 v[136:137], v114 offset:32
	ds_read_b64_tr_b16 v[138:139], v114 offset:2144
	ds_read_b64_tr_b16 v[140:141], v114 offset:64
	ds_read_b64_tr_b16 v[142:143], v114 offset:2176
	ds_read_b64_tr_b16 v[144:145], v114 offset:96
	ds_read_b64_tr_b16 v[146:147], v114 offset:2208
	s_waitcnt lgkmcnt(6)
	v_mfma_f32_16x16x32_bf16 v[2:5], v[116:119], v[132:135], v[2:5]
	s_waitcnt lgkmcnt(4)
	v_mfma_f32_16x16x32_bf16 v[6:9], v[116:119], v[136:139], v[6:9]
	s_waitcnt lgkmcnt(2)
	v_mfma_f32_16x16x32_bf16 v[10:13], v[116:119], v[140:143], v[10:13]
	s_waitcnt lgkmcnt(0)
	v_mfma_f32_16x16x32_bf16 v[14:17], v[116:119], v[144:147], v[14:17]
	v_mfma_f32_16x16x32_bf16 v[18:21], v[120:123], v[132:135], v[18:21]
	v_mfma_f32_16x16x32_bf16 v[22:25], v[120:123], v[136:139], v[22:25]
	v_mfma_f32_16x16x32_bf16 v[26:29], v[120:123], v[140:143], v[26:29]
	v_mfma_f32_16x16x32_bf16 v[30:33], v[120:123], v[144:147], v[30:33]
	v_mfma_f32_16x16x32_bf16 v[34:37], v[124:127], v[132:135], v[34:37]
	v_mfma_f32_16x16x32_bf16 v[38:41], v[124:127], v[136:139], v[38:41]
	v_mfma_f32_16x16x32_bf16 v[42:45], v[124:127], v[140:143], v[42:45]
	v_mfma_f32_16x16x32_bf16 v[46:49], v[124:127], v[144:147], v[46:49]
	v_mfma_f32_16x16x32_bf16 v[50:53], v[128:131], v[132:135], v[50:53]
	v_mfma_f32_16x16x32_bf16 v[54:57], v[128:131], v[136:139], v[54:57]
	v_mfma_f32_16x16x32_bf16 v[58:61], v[128:131], v[140:143], v[58:61]
	v_mfma_f32_16x16x32_bf16 v[62:65], v[128:131], v[144:147], v[62:65]
	ds_read_b64_tr_b16 v[116:117], v113 offset:42496
	ds_read_b64_tr_b16 v[118:119], v113 offset:43584
	ds_read_b64_tr_b16 v[120:121], v113 offset:42528
	ds_read_b64_tr_b16 v[122:123], v113 offset:43616
	ds_read_b64_tr_b16 v[124:125], v113 offset:42560
	ds_read_b64_tr_b16 v[126:127], v113 offset:43648
	ds_read_b64_tr_b16 v[128:129], v113 offset:42592
	ds_read_b64_tr_b16 v[130:131], v113 offset:43680
	ds_read_b64_tr_b16 v[132:133], v114 offset:16896
	ds_read_b64_tr_b16 v[134:135], v114 offset:19008
	ds_read_b64_tr_b16 v[136:137], v114 offset:16928
	ds_read_b64_tr_b16 v[138:139], v114 offset:19040
	ds_read_b64_tr_b16 v[140:141], v114 offset:16960
	ds_read_b64_tr_b16 v[142:143], v114 offset:19072
	ds_read_b64_tr_b16 v[144:145], v114 offset:16992
	ds_read_b64_tr_b16 v[146:147], v114 offset:19104
	s_waitcnt lgkmcnt(0)
	s_barrier
; #define LAS __attribute__((address_space(3)))
; __device__ __forceinline__ unsigned cvt_pk_bf16(float lo, float hi) { const f32x2 v = {lo, hi}; const bf16v2 r = __builtin_convertvector(v, bf16v2); return __builtin_bit_cast(unsigned, r); }
; __device__ __forceinline__ float bf_lo(unsigned u) { return __uint_as_float(u << 16); }
; __device__ __forceinline__ float bf_hi(unsigned u) { return __uint_as_float(u & 0xffff0000u); }
; #define MFMA16(a, b, c) __builtin_amdgcn_mfma_f32_16x16x32_bf16((a), (b), (c), 0, 0, 0)
; __device__ void ret_kv_phase(LAS unsigned char* lds, const bf16_t* PROJ, bf16_t* ST, const float* lgf, const float* lgb) {
;     ...
;             for (int it = 0; it < 4; ++it) { const int idx = tid + 512 * it, row = idx >> 5, ch = idx & 31; const size_t tok = (size_t)c * 256 + sub * 64 + row;
;                 *(LAS u32x4*)(Kl + row * 528 + ch * 16) = *(const u32x4*)(PROJ + pj(tok, 4096 + h * 256 + ch * 8)); }
; #pragma unroll
;             for (int it = 0; it < 2; ++it) { const int idx = tid + 512 * it, row = idx >> 4, ch = idx & 15; const int jl = sub * 64 + row; const size_t tok = (size_t)c * 256 + jl;
;                 const float z = __expf(lg * (float)(dir ? jl : 255 - jl));
;                 const u32x4 v = *(const u32x4*)(PROJ + pj(tok, 5120 + h * 256 + dvh * 128 + ch * 8)); u32x4 w;
; #pragma unroll
;                 for (int e = 0; e < 4; ++e) w[e] = cvt_pk_bf16(bf_lo(v[e]) * z, bf_hi(v[e]) * z);
;                 *(LAS u32x4*)(Vl + row * 272 + ch * 16) = w; }
;     ...
; #pragma unroll
;             for (int ks = 0; ks < 2; ++ks) {
;                 bf16x8 af[4], bfr[4];
;                 LAS unsigned char* vb = Vl + (32 * ks + 8 * g + q4) * 272 + (wr * 64) * 2 + 8 * p4;
;                 LAS unsigned char* kb = Kl + (32 * ks + 8 * g + q4) * 528 + (wc * 64) * 2 + 8 * p4;
; #pragma unroll
;                 for (int a = 0; a < 4; ++a) af[a] = tr_pair(vb + 32 * a, vb + 4 * 272 + 32 * a);
; #pragma unroll
;                 for (int bb = 0; bb < 4; ++bb) bfr[bb] = tr_pair(kb + 32 * bb, kb + 4 * 528 + 32 * bb);
; #pragma unroll
;                 for (int a = 0; a < 4; ++a)
; #pragma unroll
;                     for (int bb = 0; bb < 4; ++bb) acc[a][bb] = MFMA16(af[a], bfr[bb], acc[a][bb]);
	v_mfma_f32_16x16x32_bf16 v[2:5], v[116:119], v[132:135], v[2:5]
	v_mfma_f32_16x16x32_bf16 v[6:9], v[116:119], v[136:139], v[6:9]
	v_mfma_f32_16x16x32_bf16 v[10:13], v[116:119], v[140:143], v[10:13]
	v_mfma_f32_16x16x32_bf16 v[14:17], v[116:119], v[144:147], v[14:17]
	s_nop 0
	s_nop 0
	s_nop 0
	s_nop 0
	v_mfma_f32_16x16x32_bf16 v[18:21], v[120:123], v[132:135], v[18:21]
	s_nop 0
	s_nop 0
	s_nop 0
	v_mfma_f32_16x16x32_bf16 v[22:25], v[120:123], v[136:139], v[22:25]
	s_waitcnt vmcnt(5)
	ds_write_b128 v107, v[176:179]
	s_nop 0
	s_nop 0
	s_nop 0
	s_nop 0
	v_mfma_f32_16x16x32_bf16 v[26:29], v[120:123], v[140:143], v[26:29]
	s_nop 0
	s_nop 0
	s_nop 0
	v_mfma_f32_16x16x32_bf16 v[30:33], v[120:123], v[144:147], v[30:33]
	s_waitcnt vmcnt(4)
	ds_write_b128 v108, v[180:183]
	s_nop 0
	s_nop 0
	s_nop 0
	s_nop 0
	v_mfma_f32_16x16x32_bf16 v[34:37], v[124:127], v[132:135], v[34:37]
	s_nop 0
	s_nop 0
	s_nop 0
	v_mfma_f32_16x16x32_bf16 v[38:41], v[124:127], v[136:139], v[38:41]
	s_waitcnt vmcnt(3)
	ds_write_b128 v109, v[184:187]
	s_nop 0
	s_nop 0
	s_nop 0
	s_nop 0
	v_mfma_f32_16x16x32_bf16 v[42:45], v[124:127], v[140:143], v[42:45]
	s_nop 0
	s_nop 0
	s_nop 0
	v_mfma_f32_16x16x32_bf16 v[46:49], v[124:127], v[144:147], v[46:49]
	s_waitcnt vmcnt(2)
	ds_write_b128 v110, v[188:191]
	s_nop 0
	s_nop 0
	s_nop 0
	s_nop 0
	v_mfma_f32_16x16x32_bf16 v[50:53], v[128:131], v[132:135], v[50:53]
	s_nop 0
	s_nop 0
	s_nop 0
	v_mfma_f32_16x16x32_bf16 v[54:57], v[128:131], v[136:139], v[54:57]
	s_waitcnt vmcnt(1)
	v_lshlrev_b32_e32 v120, 16, v192
	v_and_b32_e32 v121, 0xffff0000, v192
	v_pk_mul_f32 v[120:121], v[0:1], v[120:121] op_sel_hi:[0,1]
	v_cvt_pk_bf16_f32 v192, v120, v121
	v_lshlrev_b32_e32 v120, 16, v193
	v_and_b32_e32 v121, 0xffff0000, v193
	v_pk_mul_f32 v[120:121], v[0:1], v[120:121] op_sel_hi:[0,1]
	v_cvt_pk_bf16_f32 v193, v120, v121
	v_lshlrev_b32_e32 v120, 16, v194
	v_and_b32_e32 v121, 0xffff0000, v194
	v_pk_mul_f32 v[120:121], v[0:1], v[120:121] op_sel_hi:[0,1]
	v_cvt_pk_bf16_f32 v194, v120, v121
	v_lshlrev_b32_e32 v120, 16, v195
	v_and_b32_e32 v121, 0xffff0000, v195
	v_pk_mul_f32 v[120:121], v[0:1], v[120:121] op_sel_hi:[0,1]
	v_cvt_pk_bf16_f32 v195, v120, v121
	ds_write_b128 v111, v[192:195] offset:33792
	s_nop 0
	s_nop 0
	s_nop 0
	s_nop 0
	v_cndmask_b32_e32 v0, v86, v103, vcc
	s_nop 0
	s_nop 0
	s_nop 0
	v_cvt_f32_i32_e32 v0, v0
	v_mfma_f32_16x16x32_bf16 v[58:61], v[128:131], v[140:143], v[58:61]
	v_mul_f32_e32 v0, v94, v0
	v_mul_f32_e32 v0, 0x3fb8aa3b, v0
	v_exp_f32_e32 v0, v0
	v_mfma_f32_16x16x32_bf16 v[62:65], v[128:131], v[144:147], v[62:65]
	s_waitcnt vmcnt(0)
	v_lshlrev_b32_e32 v120, 16, v196
	v_and_b32_e32 v121, 0xffff0000, v196
	v_pk_mul_f32 v[120:121], v[0:1], v[120:121] op_sel_hi:[0,1]
	v_cvt_pk_bf16_f32 v196, v120, v121
	v_lshlrev_b32_e32 v120, 16, v197
	v_and_b32_e32 v121, 0xffff0000, v197
	v_pk_mul_f32 v[120:121], v[0:1], v[120:121] op_sel_hi:[0,1]
	v_cvt_pk_bf16_f32 v197, v120, v121
	v_lshlrev_b32_e32 v120, 16, v198
	v_and_b32_e32 v121, 0xffff0000, v198
	v_pk_mul_f32 v[120:121], v[0:1], v[120:121] op_sel_hi:[0,1]
	v_cvt_pk_bf16_f32 v198, v120, v121
	v_lshlrev_b32_e32 v120, 16, v199
	v_and_b32_e32 v121, 0xffff0000, v199
	v_pk_mul_f32 v[120:121], v[0:1], v[120:121] op_sel_hi:[0,1]
	v_cvt_pk_bf16_f32 v199, v120, v121
	ds_write_b128 v112, v[196:199] offset:33792
	s_waitcnt lgkmcnt(0)
	s_barrier
	v_lshl_add_u64 v[176:177], s[12:13], 0, v[68:69]
	v_lshlrev_b64 v[176:177], 9, v[176:177]
	v_lshl_add_u64 v[176:177], v[66:67], 0, v[176:177]
	v_add_co_u32_e64 v176, s[0:1], s33, v176
	s_nop 1
	v_addc_co_u32_e64 v177, s[0:1], 0, v177, s[0:1]
	global_load_dwordx4 v[176:179], v[176:177], off
	v_lshl_add_u64 v[180:181], s[12:13], 0, v[70:71]
	v_lshlrev_b64 v[180:181], 9, v[180:181]
	v_lshl_add_u64 v[180:181], v[66:67], 0, v[180:181]
	v_add_co_u32_e64 v180, s[0:1], s33, v180
	s_nop 1
	v_addc_co_u32_e64 v181, s[0:1], 0, v181, s[0:1]
	global_load_dwordx4 v[180:183], v[180:181], off
	v_lshl_add_u64 v[184:185], s[12:13], 0, v[72:73]
	v_lshlrev_b64 v[184:185], 9, v[184:185]
	v_lshl_add_u64 v[184:185], v[66:67], 0, v[184:185]
	v_add_co_u32_e64 v184, s[0:1], s33, v184
	s_nop 1
	v_addc_co_u32_e64 v185, s[0:1], 0, v185, s[0:1]
	global_load_dwordx4 v[184:187], v[184:185], off
	v_lshl_add_u64 v[188:189], s[12:13], 0, v[74:75]
	v_lshlrev_b64 v[188:189], 9, v[188:189]
	v_lshl_add_u64 v[188:189], v[66:67], 0, v[188:189]
	v_add_co_u32_e64 v188, s[0:1], s33, v188
	s_nop 1
	v_addc_co_u32_e64 v189, s[0:1], 0, v189, s[0:1]
	global_load_dwordx4 v[188:191], v[188:189], off
	v_lshl_add_u64 v[192:193], s[6:7], 0, v[88:89]
	v_lshlrev_b64 v[192:193], 9, v[192:193]
	v_lshl_add_u64 v[192:193], v[92:93], 0, v[192:193]
	v_add_co_u32_e64 v192, s[0:1], s33, v192
	s_nop 1
	v_addc_co_u32_e64 v193, s[0:1], 0, v193, s[0:1]
	global_load_dwordx4 v[192:195], v[192:193], off
	ds_read_b64_tr_b16 v[118:119], v113 offset:34880
	ds_read_b64_tr_b16 v[116:117], v113 offset:33792
	ds_read_b64_tr_b16 v[120:121], v113 offset:33824
	ds_read_b64_tr_b16 v[122:123], v113 offset:34912
	ds_read_b64_tr_b16 v[124:125], v113 offset:33856
	ds_read_b64_tr_b16 v[126:127], v113 offset:34944
	ds_read_b64_tr_b16 v[128:129], v113 offset:33888
	ds_read_b64_tr_b16 v[130:131], v113 offset:34976
	ds_read_b64_tr_b16 v[134:135], v114 offset:2112
	ds_read_b64_tr_b16 v[132:133], v114
	ds_read_b64_tr_b16 v[136:137], v114 offset:32
	ds_read_b64_tr_b16 v[138:139], v114 offset:2144
	ds_read_b64_tr_b16 v[140:141], v114 offset:64
	ds_read_b64_tr_b16 v[142:143], v114 offset:2176
	ds_read_b64_tr_b16 v[144:145], v114 offset:96
	ds_read_b64_tr_b16 v[146:147], v114 offset:2208
	s_waitcnt lgkmcnt(6)
; #define LAS __attribute__((address_space(3)))
; __device__ __forceinline__ unsigned cvt_pk_bf16(float lo, float hi) { const f32x2 v = {lo, hi}; const bf16v2 r = __builtin_convertvector(v, bf16v2); return __builtin_bit_cast(unsigned, r); }
; __device__ __forceinline__ float bf_lo(unsigned u) { return __uint_as_float(u << 16); }
; __device__ __forceinline__ float bf_hi(unsigned u) { return __uint_as_float(u & 0xffff0000u); }
; __device__ __forceinline__ int obid() { int b = blockIdx.x; asm volatile("" : "+s"(b)); return b; }
; __device__ void ret_kv_phase(LAS unsigned char* lds, const bf16_t* PROJ, bf16_t* ST, const float* lgf, const float* lgb) {
;     ...
;     for (int item = obid(); item < 1536; item += gridDim.x) {
;     ...
;             for (int it = 0; it < 4; ++it) { const int idx = tid + 512 * it, row = idx >> 5, ch = idx & 31; const size_t tok = (size_t)c * 256 + sub * 64 + row;
;                 *(LAS u32x4*)(Kl + row * 528 + ch * 16) = *(const u32x4*)(PROJ + pj(tok, 4096 + h * 256 + ch * 8)); }
; #pragma unroll
;             for (int it = 0; it < 2; ++it) { const int idx = tid + 512 * it, row = idx >> 4, ch = idx & 15; const int jl = sub * 64 + row; const size_t tok = (size_t)c * 256 + jl;
;                 const float z = __expf(lg * (float)(dir ? jl : 255 - jl));
;                 const u32x4 v = *(const u32x4*)(PROJ + pj(tok, 5120 + h * 256 + dvh * 128 + ch * 8)); u32x4 w;
; #pragma unroll
;                 for (int e = 0; e < 4; ++e) w[e] = cvt_pk_bf16(bf_lo(v[e]) * z, bf_hi(v[e]) * z);
;                 *(LAS u32x4*)(Vl + row * 272 + ch * 16) = w; }
;     ...
; #pragma unroll
;             for (int ks = 0; ks < 2; ++ks) {
;                 bf16x8 af[4], bfr[4];
;                 LAS unsigned char* vb = Vl + (32 * ks + 8 * g + q4) * 272 + (wr * 64) * 2 + 8 * p4;
;                 LAS unsigned char* kb = Kl + (32 * ks + 8 * g + q4) * 528 + (wc * 64) * 2 + 8 * p4;
; #pragma unroll
;                 for (int a = 0; a < 4; ++a) af[a] = tr_pair(vb + 32 * a, vb + 4 * 272 + 32 * a);
; #pragma unroll
;                 for (int bb = 0; bb < 4; ++bb) bfr[bb] = tr_pair(kb + 32 * bb, kb + 4 * 528 + 32 * bb);
; #pragma unroll
;                 for (int a = 0; a < 4; ++a)
; #pragma unroll
;                     for (int bb = 0; bb < 4; ++bb) acc[a][bb] = MFMA16(af[a], bfr[bb], acc[a][bb]);
;     ...
;         bf16_t* sp = ST + ((size_t)((dir * 96 + c) * 4 + h)) * 65536;
	v_mfma_f32_16x16x32_bf16 v[2:5], v[116:119], v[132:135], v[2:5]
	v_cndmask_b32_e32 v0, v88, v104, vcc
	v_cvt_f32_i32_e32 v0, v0
	v_mul_f32_e32 v0, v94, v0
	s_waitcnt lgkmcnt(4)
	v_mfma_f32_16x16x32_bf16 v[6:9], v[116:119], v[136:139], v[6:9]
	v_mul_f32_e32 v0, 0x3fb8aa3b, v0
	v_exp_f32_e32 v0, v0
	s_waitcnt lgkmcnt(2)
	v_mfma_f32_16x16x32_bf16 v[10:13], v[116:119], v[140:143], v[10:13]
	s_waitcnt lgkmcnt(0)
	v_mfma_f32_16x16x32_bf16 v[14:17], v[116:119], v[144:147], v[14:17]
	v_mfma_f32_16x16x32_bf16 v[116:119], v[124:127], v[132:135], v[34:37]
	v_mfma_f32_16x16x32_bf16 v[18:21], v[120:123], v[132:135], v[18:21]
	v_mfma_f32_16x16x32_bf16 v[22:25], v[120:123], v[136:139], v[22:25]
	v_mfma_f32_16x16x32_bf16 v[26:29], v[120:123], v[140:143], v[26:29]
	v_mfma_f32_16x16x32_bf16 v[30:33], v[120:123], v[144:147], v[30:33]
	v_mfma_f32_16x16x32_bf16 v[120:123], v[124:127], v[136:139], v[38:41]
	v_mfma_f32_16x16x32_bf16 v[148:151], v[124:127], v[140:143], v[42:45]
	v_mfma_f32_16x16x32_bf16 v[124:127], v[124:127], v[144:147], v[46:49]
	v_mfma_f32_16x16x32_bf16 v[132:135], v[128:131], v[132:135], v[50:53]
	v_mfma_f32_16x16x32_bf16 v[136:139], v[128:131], v[136:139], v[54:57]
	v_mfma_f32_16x16x32_bf16 v[140:143], v[128:131], v[140:143], v[58:61]
	v_mfma_f32_16x16x32_bf16 v[128:131], v[128:131], v[144:147], v[62:65]
	ds_read_b64_tr_b16 v[34:35], v113 offset:42496
	ds_read_b64_tr_b16 v[36:37], v113 offset:43584
	ds_read_b64_tr_b16 v[144:145], v113 offset:42528
	ds_read_b64_tr_b16 v[146:147], v113 offset:43616
	ds_read_b64_tr_b16 v[152:153], v113 offset:42560
	ds_read_b64_tr_b16 v[154:155], v113 offset:43648
	ds_read_b64_tr_b16 v[156:157], v113 offset:42592
	ds_read_b64_tr_b16 v[158:159], v113 offset:43680
	ds_read_b64_tr_b16 v[160:161], v114 offset:16896
	ds_read_b64_tr_b16 v[162:163], v114 offset:19008
	ds_read_b64_tr_b16 v[164:165], v114 offset:16928
	ds_read_b64_tr_b16 v[166:167], v114 offset:19040
	ds_read_b64_tr_b16 v[168:169], v114 offset:16960
	ds_read_b64_tr_b16 v[170:171], v114 offset:19072
	ds_read_b64_tr_b16 v[172:173], v114 offset:16992
	ds_read_b64_tr_b16 v[174:175], v114 offset:19104
	s_waitcnt lgkmcnt(0)
	s_barrier
	v_mfma_f32_16x16x32_bf16 v[62:65], v[34:37], v[160:163], v[2:5]
	v_mfma_f32_16x16x32_bf16 v[2:5], v[152:155], v[160:163], v[116:119]
	s_nop 2
	s_nop 0
	s_nop 0
	s_nop 0
	s_nop 0
	v_mfma_f32_16x16x32_bf16 v[58:61], v[34:37], v[164:167], v[6:9]
	s_nop 0
	s_nop 0
	s_nop 0
	v_mfma_f32_16x16x32_bf16 v[6:9], v[152:155], v[164:167], v[120:123]
	s_waitcnt vmcnt(4)
	ds_write_b128 v107, v[176:179]
	s_nop 0
	s_nop 0
	s_nop 0
	s_nop 0
	v_mfma_f32_16x16x32_bf16 v[54:57], v[34:37], v[168:171], v[10:13]
	s_nop 0
	s_nop 0
	s_nop 0
	v_mfma_f32_16x16x32_bf16 v[50:53], v[34:37], v[172:175], v[14:17]
	s_waitcnt vmcnt(3)
	ds_write_b128 v108, v[180:183]
	s_nop 0
	s_nop 0
	s_nop 0
	s_nop 0
	v_mfma_f32_16x16x32_bf16 v[38:41], v[144:147], v[160:163], v[18:21]
	s_nop 0
	s_nop 0
	s_nop 0
	v_mfma_f32_16x16x32_bf16 v[42:45], v[144:147], v[164:167], v[22:25]
	s_waitcnt vmcnt(2)
	ds_write_b128 v109, v[184:187]
	s_nop 0
	s_nop 0
	s_nop 0
	s_nop 0
	v_mfma_f32_16x16x32_bf16 v[46:49], v[144:147], v[168:171], v[26:29]
	s_nop 0
	s_nop 0
	s_nop 0
	v_mfma_f32_16x16x32_bf16 v[34:37], v[144:147], v[172:175], v[30:33]
	s_waitcnt vmcnt(1)
	ds_write_b128 v110, v[188:191]
	s_nop 0
	s_nop 0
	s_nop 0
	s_nop 0
	v_mfma_f32_16x16x32_bf16 v[14:17], v[152:155], v[172:175], v[124:127]
	s_nop 0
	s_nop 0
	s_nop 0
	v_mfma_f32_16x16x32_bf16 v[18:21], v[156:159], v[160:163], v[132:135]
	s_add_i32 s0, s4, s17
	s_lshl_b32 s0, s0, 2
	s_or_b32 s0, s0, s16
	v_mfma_f32_16x16x32_bf16 v[22:25], v[156:159], v[164:167], v[136:139]
	s_ashr_i32 s1, s0, 31
	s_lshl_b64 s[0:1], s[0:1], 17
	s_add_u32 s0, s84, s0
	v_mfma_f32_16x16x32_bf16 v[26:29], v[156:159], v[168:171], v[140:143]
	s_addc_u32 s1, s85, s1
	s_add_i32 s14, s14, s10
	s_add_i32 s15, s15, s18
	v_mfma_f32_16x16x32_bf16 v[30:33], v[156:159], v[172:175], v[128:131]
	s_cmpk_gt_i32 s14, 0x5ff
	s_waitcnt vmcnt(0)
	v_lshlrev_b32_e32 v120, 16, v192
	v_and_b32_e32 v121, 0xffff0000, v192
	v_pk_mul_f32 v[120:121], v[0:1], v[120:121] op_sel_hi:[0,1]
	v_cvt_pk_bf16_f32 v192, v120, v121
	v_lshlrev_b32_e32 v120, 16, v193
	v_and_b32_e32 v121, 0xffff0000, v193
	v_pk_mul_f32 v[120:121], v[0:1], v[120:121] op_sel_hi:[0,1]
	v_cvt_pk_bf16_f32 v193, v120, v121
	v_lshlrev_b32_e32 v120, 16, v194
	v_and_b32_e32 v121, 0xffff0000, v194
	v_pk_mul_f32 v[120:121], v[0:1], v[120:121] op_sel_hi:[0,1]
	v_cvt_pk_bf16_f32 v194, v120, v121
	v_lshlrev_b32_e32 v120, 16, v195
	v_and_b32_e32 v121, 0xffff0000, v195
	v_pk_mul_f32 v[120:121], v[0:1], v[120:121] op_sel_hi:[0,1]
	v_cndmask_b32_e32 v0, v90, v105, vcc
	v_cvt_f32_i32_e32 v0, v0
	v_cvt_pk_bf16_f32 v195, v120, v121
	ds_write_b128 v111, v[192:195] offset:33792
	v_mfma_f32_16x16x32_bf16 v[10:13], v[152:155], v[168:171], v[148:151]
	v_mul_f32_e32 v0, v94, v0
	v_lshl_add_u64 v[94:95], s[6:7], 0, v[90:91]
	v_lshlrev_b64 v[94:95], 9, v[94:95]
	v_lshl_add_u64 v[92:93], v[92:93], 0, v[94:95]
	v_add_co_u32_e32 v92, vcc, s33, v92
	v_mul_f32_e32 v0, 0x3fb8aa3b, v0
	s_nop 0
	v_addc_co_u32_e32 v93, vcc, 0, v93, vcc
	global_load_dwordx4 v[92:95], v[92:93], off
	v_exp_f32_e32 v0, v0
	s_waitcnt vmcnt(0)
	v_lshlrev_b32_e32 v116, 16, v92
	v_and_b32_e32 v117, 0xffff0000, v92
	v_pk_mul_f32 v[116:117], v[0:1], v[116:117] op_sel_hi:[0,1]
	v_cvt_pk_bf16_f32 v92, v116, v117
	v_lshlrev_b32_e32 v116, 16, v93
	v_and_b32_e32 v117, 0xffff0000, v93
	v_pk_mul_f32 v[116:117], v[0:1], v[116:117] op_sel_hi:[0,1]
	v_cvt_pk_bf16_f32 v93, v116, v117
	v_lshlrev_b32_e32 v116, 16, v94
	v_and_b32_e32 v117, 0xffff0000, v94
	v_pk_mul_f32 v[116:117], v[0:1], v[116:117] op_sel_hi:[0,1]
	v_cvt_pk_bf16_f32 v94, v116, v117
	v_lshlrev_b32_e32 v116, 16, v95
	v_and_b32_e32 v117, 0xffff0000, v95
	v_pk_mul_f32 v[116:117], v[0:1], v[116:117] op_sel_hi:[0,1]
	v_cvt_pk_bf16_f32 v95, v116, v117
	ds_write_b128 v112, v[92:95] offset:33792
	s_waitcnt lgkmcnt(0)
	s_barrier
; #define LAS __attribute__((address_space(3)))
; #define MFMA16(a, b, c) __builtin_amdgcn_mfma_f32_16x16x32_bf16((a), (b), (c), 0, 0, 0)
; __device__ void ret_kv_phase(LAS unsigned char* lds, const bf16_t* PROJ, bf16_t* ST, const float* lgf, const float* lgb) {
;     ...
; #pragma unroll
;             for (int ks = 0; ks < 2; ++ks) {
;                 bf16x8 af[4], bfr[4];
;                 LAS unsigned char* vb = Vl + (32 * ks + 8 * g + q4) * 272 + (wr * 64) * 2 + 8 * p4;
;                 LAS unsigned char* kb = Kl + (32 * ks + 8 * g + q4) * 528 + (wc * 64) * 2 + 8 * p4;
; #pragma unroll
;                 for (int a = 0; a < 4; ++a) af[a] = tr_pair(vb + 32 * a, vb + 4 * 272 + 32 * a);
; #pragma unroll
;                 for (int bb = 0; bb < 4; ++bb) bfr[bb] = tr_pair(kb + 32 * bb, kb + 4 * 528 + 32 * bb);
; #pragma unroll
;                 for (int a = 0; a < 4; ++a)
; #pragma unroll
;                     for (int bb = 0; bb < 4; ++bb) acc[a][bb] = MFMA16(af[a], bfr[bb], acc[a][bb]);
	ds_read_b64_tr_b16 v[94:95], v113 offset:34880
	ds_read_b64_tr_b16 v[92:93], v113 offset:33792
	ds_read_b64_tr_b16 v[116:117], v113 offset:33824
	ds_read_b64_tr_b16 v[118:119], v113 offset:34912
	ds_read_b64_tr_b16 v[120:121], v113 offset:33856
	ds_read_b64_tr_b16 v[122:123], v113 offset:34944
	ds_read_b64_tr_b16 v[124:125], v113 offset:33888
	ds_read_b64_tr_b16 v[126:127], v113 offset:34976
	ds_read_b64_tr_b16 v[130:131], v114 offset:2112
	ds_read_b64_tr_b16 v[128:129], v114
	ds_read_b64_tr_b16 v[132:133], v114 offset:32
	ds_read_b64_tr_b16 v[134:135], v114 offset:2144
	ds_read_b64_tr_b16 v[136:137], v114 offset:64
	ds_read_b64_tr_b16 v[138:139], v114 offset:2176
	ds_read_b64_tr_b16 v[140:141], v114 offset:96
	ds_read_b64_tr_b16 v[142:143], v114 offset:2208
	s_waitcnt lgkmcnt(6)
	v_mfma_f32_16x16x32_bf16 v[62:65], v[92:95], v[128:131], v[62:65]
	v_add_u32_e32 v0, s5, v97
	s_waitcnt lgkmcnt(4)
	v_mfma_f32_16x16x32_bf16 v[58:61], v[92:95], v[132:135], v[58:61]
	s_waitcnt lgkmcnt(2)
	v_mfma_f32_16x16x32_bf16 v[54:57], v[92:95], v[136:139], v[54:57]
	s_waitcnt lgkmcnt(0)
	v_mfma_f32_16x16x32_bf16 v[50:53], v[92:95], v[140:143], v[50:53]
	v_mfma_f32_16x16x32_bf16 v[38:41], v[116:119], v[128:131], v[38:41]
	v_mfma_f32_16x16x32_bf16 v[42:45], v[116:119], v[132:135], v[42:45]
	v_mfma_f32_16x16x32_bf16 v[92:95], v[116:119], v[136:139], v[46:49]
	v_mfma_f32_16x16x32_bf16 v[34:37], v[116:119], v[140:143], v[34:37]
	v_mfma_f32_16x16x32_bf16 v[2:5], v[120:123], v[128:131], v[2:5]
	v_mfma_f32_16x16x32_bf16 v[6:9], v[120:123], v[132:135], v[6:9]
	v_mfma_f32_16x16x32_bf16 v[10:13], v[120:123], v[136:139], v[10:13]
	v_mfma_f32_16x16x32_bf16 v[14:17], v[120:123], v[140:143], v[14:17]
	v_mfma_f32_16x16x32_bf16 v[116:119], v[124:127], v[128:131], v[18:21]
	v_mfma_f32_16x16x32_bf16 v[120:123], v[124:127], v[132:135], v[22:25]
	v_mfma_f32_16x16x32_bf16 v[128:131], v[124:127], v[136:139], v[26:29]
	v_mfma_f32_16x16x32_bf16 v[124:127], v[124:127], v[140:143], v[30:33]
	ds_read_b64_tr_b16 v[18:19], v113 offset:42496
	ds_read_b64_tr_b16 v[20:21], v113 offset:43584
	ds_read_b64_tr_b16 v[22:23], v113 offset:42528
	ds_read_b64_tr_b16 v[24:25], v113 offset:43616
	ds_read_b64_tr_b16 v[132:133], v113 offset:42560
	ds_read_b64_tr_b16 v[134:135], v113 offset:43648
	ds_read_b64_tr_b16 v[136:137], v113 offset:42592
	ds_read_b64_tr_b16 v[138:139], v113 offset:43680
	ds_read_b64_tr_b16 v[140:141], v114 offset:16896
	ds_read_b64_tr_b16 v[142:143], v114 offset:19008
	ds_read_b64_tr_b16 v[144:145], v114 offset:16928
	ds_read_b64_tr_b16 v[146:147], v114 offset:19040
	ds_read_b64_tr_b16 v[148:149], v114 offset:16960
	ds_read_b64_tr_b16 v[150:151], v114 offset:19072
	ds_read_b64_tr_b16 v[152:153], v114 offset:16992
	ds_read_b64_tr_b16 v[154:155], v114 offset:19104
	s_waitcnt lgkmcnt(0)
	s_barrier
; __device__ __forceinline__ unsigned cvt_pk_bf16(float lo, float hi) { const f32x2 v = {lo, hi}; const bf16v2 r = __builtin_convertvector(v, bf16v2); return __builtin_bit_cast(unsigned, r); }
; #define MFMA16(a, b, c) __builtin_amdgcn_mfma_f32_16x16x32_bf16((a), (b), (c), 0, 0, 0)
; __device__ void ret_kv_phase(LAS unsigned char* lds, const bf16_t* PROJ, bf16_t* ST, const float* lgf, const float* lgb) {
;     ...
;                 for (int a = 0; a < 4; ++a)
; #pragma unroll
;                     for (int bb = 0; bb < 4; ++bb) acc[a][bb] = MFMA16(af[a], bfr[bb], acc[a][bb]);
;             }
;             __syncthreads();
;         }
;         bf16_t* sp = ST + ((size_t)((dir * 96 + c) * 4 + h)) * 65536;
; #pragma unroll
;         for (int a = 0; a < 4; ++a)
; #pragma unroll
;             for (int j = 0; j < 4; ++j) { const int dv = dvh * 128 + wr * 64 + 16 * a + 4 * g + j;
; #pragma unroll
;                 for (int bb = 0; bb < 4; ++bb) sp[dv * 256 + wc * 64 + 16 * bb + fr] = (bf16_t)(cvt_pk_bf16(acc[a][bb][j], 0.f) & 0xffffu); }
	v_mfma_f32_16x16x32_bf16 v[62:65], v[18:21], v[140:143], v[62:65]
	v_mfma_f32_16x16x32_bf16 v[58:61], v[18:21], v[144:147], v[58:61]
	v_mfma_f32_16x16x32_bf16 v[54:57], v[18:21], v[148:151], v[54:57]
	v_mfma_f32_16x16x32_bf16 v[46:49], v[22:25], v[140:143], v[38:41]
	v_mfma_f32_16x16x32_bf16 v[38:41], v[22:25], v[148:151], v[92:95]
	s_nop 2
	v_lshl_or_b32 v92, v0, 8, v106
	v_mfma_f32_16x16x32_bf16 v[50:53], v[18:21], v[152:155], v[50:53]
	v_ashrrev_i32_e32 v93, 31, v92
	v_cvt_pk_bf16_f32 v0, v62, s0
	v_lshl_add_u64 v[92:93], v[92:93], 1, s[0:1]
	global_store_short v[92:93], v0, off
	v_cvt_pk_bf16_f32 v0, v58, s0
	global_store_short v[92:93], v0, off offset:32
	v_cvt_pk_bf16_f32 v0, v54, s0
	global_store_short v[92:93], v0, off offset:64
	v_cvt_pk_bf16_f32 v0, v50, s0
	global_store_short v[92:93], v0, off offset:96
	v_cvt_pk_bf16_f32 v0, v63, s0
	global_store_short v[92:93], v0, off offset:512
	v_cvt_pk_bf16_f32 v0, v59, s0
	global_store_short v[92:93], v0, off offset:544
	v_cvt_pk_bf16_f32 v0, v55, s0
	global_store_short v[92:93], v0, off offset:576
	v_cvt_pk_bf16_f32 v0, v51, s0
	global_store_short v[92:93], v0, off offset:608
	v_cvt_pk_bf16_f32 v0, v64, s0
	global_store_short v[92:93], v0, off offset:1024
	v_cvt_pk_bf16_f32 v0, v60, s0
	global_store_short v[92:93], v0, off offset:1056
	v_cvt_pk_bf16_f32 v0, v56, s0
	global_store_short v[92:93], v0, off offset:1088
	v_cvt_pk_bf16_f32 v0, v52, s0
	global_store_short v[92:93], v0, off offset:1120
	v_cvt_pk_bf16_f32 v0, v65, s0
	v_mfma_f32_16x16x32_bf16 v[42:45], v[22:25], v[144:147], v[42:45]
	global_store_short v[92:93], v0, off offset:1536
	v_cvt_pk_bf16_f32 v0, v61, s0
	global_store_short v[92:93], v0, off offset:1568
	v_cvt_pk_bf16_f32 v0, v57, s0
	v_mfma_f32_16x16x32_bf16 v[34:37], v[22:25], v[152:155], v[34:37]
	global_store_short v[92:93], v0, off offset:1600
	v_cvt_pk_bf16_f32 v0, v53, s0
	v_add_co_u32_e32 v50, vcc, s22, v92
	global_store_short v[92:93], v0, off offset:1632
	v_cvt_pk_bf16_f32 v0, v46, s0
	v_addc_co_u32_e32 v51, vcc, 0, v93, vcc
	global_store_short v[50:51], v0, off
	v_cvt_pk_bf16_f32 v0, v42, s0
	global_store_short v[50:51], v0, off offset:32
	v_cvt_pk_bf16_f32 v0, v38, s0
	global_store_short v[50:51], v0, off offset:64
	v_cvt_pk_bf16_f32 v0, v34, s0
	global_store_short v[50:51], v0, off offset:96
	v_cvt_pk_bf16_f32 v0, v47, s0
	global_store_short v[50:51], v0, off offset:512
	v_cvt_pk_bf16_f32 v0, v43, s0
	global_store_short v[50:51], v0, off offset:544
	v_cvt_pk_bf16_f32 v0, v39, s0
	global_store_short v[50:51], v0, off offset:576
	v_cvt_pk_bf16_f32 v0, v35, s0
	global_store_short v[50:51], v0, off offset:608
	v_cvt_pk_bf16_f32 v0, v48, s0
	global_store_short v[50:51], v0, off offset:1024
	v_cvt_pk_bf16_f32 v0, v44, s0
	global_store_short v[50:51], v0, off offset:1056
	v_cvt_pk_bf16_f32 v0, v40, s0
	global_store_short v[50:51], v0, off offset:1088
	v_cvt_pk_bf16_f32 v0, v36, s0
	v_mfma_f32_16x16x32_bf16 v[30:33], v[132:135], v[140:143], v[2:5]
	global_store_short v[50:51], v0, off offset:1120
	v_cvt_pk_bf16_f32 v0, v49, s0
	global_store_short v[50:51], v0, off offset:1536
	v_mfma_f32_16x16x32_bf16 v[26:29], v[132:135], v[144:147], v[6:9]
	v_cvt_pk_bf16_f32 v0, v45, s0
	global_store_short v[50:51], v0, off offset:1568
	v_cvt_pk_bf16_f32 v0, v41, s0
	v_mfma_f32_16x16x32_bf16 v[22:25], v[132:135], v[148:151], v[10:13]
	global_store_short v[50:51], v0, off offset:1600
	v_cvt_pk_bf16_f32 v0, v37, s0
	v_add_co_u32_e32 v34, vcc, s23, v92
	v_mfma_f32_16x16x32_bf16 v[18:21], v[132:135], v[152:155], v[14:17]
	global_store_short v[50:51], v0, off offset:1632
	v_cvt_pk_bf16_f32 v0, v30, s0
	v_addc_co_u32_e32 v35, vcc, 0, v93, vcc
	global_store_short v[34:35], v0, off
	v_cvt_pk_bf16_f32 v0, v26, s0
	global_store_short v[34:35], v0, off offset:32
	v_cvt_pk_bf16_f32 v0, v22, s0
	global_store_short v[34:35], v0, off offset:64
	v_cvt_pk_bf16_f32 v0, v18, s0
	global_store_short v[34:35], v0, off offset:96
	v_cvt_pk_bf16_f32 v0, v31, s0
	global_store_short v[34:35], v0, off offset:512
	v_cvt_pk_bf16_f32 v0, v27, s0
	global_store_short v[34:35], v0, off offset:544
	v_cvt_pk_bf16_f32 v0, v23, s0
	global_store_short v[34:35], v0, off offset:576
	v_cvt_pk_bf16_f32 v0, v19, s0
	global_store_short v[34:35], v0, off offset:608
	v_cvt_pk_bf16_f32 v0, v32, s0
	global_store_short v[34:35], v0, off offset:1024
	v_cvt_pk_bf16_f32 v0, v28, s0
	global_store_short v[34:35], v0, off offset:1056
	v_cvt_pk_bf16_f32 v0, v24, s0
	global_store_short v[34:35], v0, off offset:1088
	v_cvt_pk_bf16_f32 v0, v20, s0
	v_mfma_f32_16x16x32_bf16 v[14:17], v[136:139], v[140:143], v[116:119]
	global_store_short v[34:35], v0, off offset:1120
	v_cvt_pk_bf16_f32 v0, v33, s0
	global_store_short v[34:35], v0, off offset:1536
	v_mfma_f32_16x16x32_bf16 v[10:13], v[136:139], v[144:147], v[120:123]
	v_cvt_pk_bf16_f32 v0, v29, s0
	global_store_short v[34:35], v0, off offset:1568
	v_cvt_pk_bf16_f32 v0, v25, s0
	v_mfma_f32_16x16x32_bf16 v[6:9], v[136:139], v[148:151], v[128:131]
	global_store_short v[34:35], v0, off offset:1600
	v_cvt_pk_bf16_f32 v0, v21, s0
	v_add_co_u32_e32 v18, vcc, s24, v92
	v_mfma_f32_16x16x32_bf16 v[2:5], v[136:139], v[152:155], v[124:127]
	global_store_short v[34:35], v0, off offset:1632
	v_cvt_pk_bf16_f32 v0, v14, s0
	v_addc_co_u32_e32 v19, vcc, 0, v93, vcc
	global_store_short v[18:19], v0, off
	v_cvt_pk_bf16_f32 v0, v10, s0
	global_store_short v[18:19], v0, off offset:32
	v_cvt_pk_bf16_f32 v0, v6, s0
	global_store_short v[18:19], v0, off offset:64
	v_cvt_pk_bf16_f32 v0, v2, s0
	global_store_short v[18:19], v0, off offset:96
	v_cvt_pk_bf16_f32 v0, v15, s0
	global_store_short v[18:19], v0, off offset:512
	v_cvt_pk_bf16_f32 v0, v11, s0
	global_store_short v[18:19], v0, off offset:544
	v_cvt_pk_bf16_f32 v0, v7, s0
	global_store_short v[18:19], v0, off offset:576
	v_cvt_pk_bf16_f32 v0, v3, s0
	global_store_short v[18:19], v0, off offset:608
	v_cvt_pk_bf16_f32 v0, v16, s0
	global_store_short v[18:19], v0, off offset:1024
	v_cvt_pk_bf16_f32 v0, v12, s0
	global_store_short v[18:19], v0, off offset:1056
	v_cvt_pk_bf16_f32 v0, v8, s0
	global_store_short v[18:19], v0, off offset:1088
	v_cvt_pk_bf16_f32 v0, v4, s0
	global_store_short v[18:19], v0, off offset:1120
	v_cvt_pk_bf16_f32 v0, v17, s0
	global_store_short v[18:19], v0, off offset:1536
	v_cvt_pk_bf16_f32 v0, v13, s0
	global_store_short v[18:19], v0, off offset:1568
	v_cvt_pk_bf16_f32 v0, v9, s0
	global_store_short v[18:19], v0, off offset:1600
	v_cvt_pk_bf16_f32 v0, v5, s0
	global_store_short v[18:19], v0, off offset:1632
	s_cbranch_scc0 .LBB0_370
